# wout and wxo residual epilogues: 16 residual loads hoisted to the epilogue head and waited once (ladder of load/wait-all removed), on top of the ffn2 epilogue change
# speedup vs baseline: 1.0098x; 1.0020x over previous
; #define PG8_LAS __attribute__((address_space(3)))
; __device__ __forceinline__ float sq4(const f32x4 v) { return (v[0] * v[0] + v[1] * v[1]) + (v[2] * v[2] + v[3] * v[3]); }
; __device__ __forceinline__ u32x4 pack8(const f32x4 a, const f32x4 b) { u32x4 w; w.x = cvt_pk_bf16(a[0], a[1]); w.y = cvt_pk_bf16(a[2], a[3]); w.z = cvt_pk_bf16(b[0], b[1]); w.w = cvt_pk_bf16(b[2], b[3]); return w; }
;     __device__ __forceinline__ void operator()(const f32x4 (&acc)[2][2][4][2], const Unit& u, int wr_, int wc_, int fr_, int fq_) const {
;         int ln_; asm volatile("v_mbcnt_lo_u32_b32 %0, -1, 0\n\tv_mbcnt_hi_u32_b32 %0, -1, %0" : "=v"(ln_));
;         const int fr = ln_ & 15, fq = ln_ >> 4; (void)fr_; (void)fq_;
;         int wr = wr_, wc = wc_; asm volatile("" : "+s"(wr), "+s"(wc));
;         const int col0 = u.pn * BM + wc * 32 + 8 * fq;
;         PG8_LAS float* const xw = X + (wr * 64 + fr) * 4 + wc; const PG8_LAS float* const xr = X + (wr * 64 + fr) * 4;
; #pragma unroll
;         for (int ai = 0; ai < 2; ++ai)
; #pragma unroll
;             for (int m = 0; m < 4; ++m) {
;                 const int row = u.pm * BM + ai * HALF + wr * 64 + m * 16 + fr; const size_t off = (size_t)row * 1024 + col0;
;                 float s = 0.f;
; #pragma unroll
;                 for (int bj = 0; bj < 2; ++bj) {
;                     f32x4 b0, b1;
;                     const size_t boff = (size_t)row * base_ld + col0 + bj * HALF;
;                     if (BASE_BF16) unpack8(*(const u32x4*)((const bf16_t*)base + boff), b0, b1);
;                     else { b0 = *(const f32x4*)((const float*)base + boff); b1 = *(const f32x4*)((const float*)base + boff + 4); }
;                     const f32x4 h0 = b0 + acc[ai][bj][m][0] * ascale, h1 = b1 + acc[ai][bj][m][1] * ascale;
;                     st16_wt((hb + (size_t)row * hb_ld + col0 + bj * HALF), pack8(h0, h1));
;                     s += sq4(h0) + sq4(h1);
;                 }
;                 s += __shfl_xor(s, 16); s += __shfl_xor(s, 32);
;                 if (fq == 0) xw[(ai * HALF + m * 16) * 4] = s;
;             }
.LBB0_1653:
	v_mbcnt_lo_u32_b32 v149, -1, 0
	v_mbcnt_hi_u32_b32 v149, -1, v149
	s_mov_b32 s0, s51
	v_and_b32_e32 v166, 15, v149
	s_mov_b32 s19, s59
	s_lshl_b32 s7, s7, 8
	s_lshl_b32 s1, s6, 8
	s_lshl_b32 s4, s19, 5
	v_ashrrev_i32_e32 v140, 1, v149
	s_lshl_b32 s17, s0, 6
	v_or_b32_e32 v141, s7, v166
	v_and_b32_e32 v140, -8, v140
	s_add_i32 s4, s4, s1
	v_add_u32_e32 v142, s17, v141
	v_add_u32_e32 v140, s4, v140
	v_ashrrev_i32_e32 v143, 31, v142
	v_ashrrev_i32_e32 v141, 31, v140
	v_lshlrev_b64 v[154:155], 12, v[142:143]
	v_lshl_add_u64 v[150:151], s[10:11], 0, v[154:155]
	v_lshlrev_b64 v[140:141], 1, v[140:141]
	v_mov_b32_e32 v240, v142
	v_ashrrev_i32_e32 v241, 31, v240
	v_lshlrev_b64 v[240:241], 12, v[240:241]
	v_lshl_add_u64 v[240:241], s[10:11], 0, v[240:241]
	v_lshl_add_u64 v[242:243], v[240:241], 0, v[140:141]
	global_load_dwordx4 v[172:175], v[242:243], off
	global_load_dwordx4 v[176:179], v[242:243], off offset:256
	v_or_b32_e32 v240, 16, v142
	v_ashrrev_i32_e32 v241, 31, v240
	v_lshlrev_b64 v[240:241], 12, v[240:241]
	v_lshl_add_u64 v[240:241], s[10:11], 0, v[240:241]
	v_lshl_add_u64 v[242:243], v[240:241], 0, v[140:141]
	global_load_dwordx4 v[180:183], v[242:243], off
	global_load_dwordx4 v[188:191], v[242:243], off offset:256
	v_or_b32_e32 v240, 32, v142
	v_ashrrev_i32_e32 v241, 31, v240
	v_lshlrev_b64 v[240:241], 12, v[240:241]
	v_lshl_add_u64 v[240:241], s[10:11], 0, v[240:241]
	v_lshl_add_u64 v[242:243], v[240:241], 0, v[140:141]
	global_load_dwordx4 v[192:195], v[242:243], off
	global_load_dwordx4 v[196:199], v[242:243], off offset:256
	v_or_b32_e32 v240, 48, v142
	v_ashrrev_i32_e32 v241, 31, v240
	v_lshlrev_b64 v[240:241], 12, v[240:241]
	v_lshl_add_u64 v[240:241], s[10:11], 0, v[240:241]
	v_lshl_add_u64 v[242:243], v[240:241], 0, v[140:141]
	global_load_dwordx4 v[200:203], v[242:243], off
	global_load_dwordx4 v[204:207], v[242:243], off offset:256
	v_add_u32_e32 v240, 0x80, v142
	v_ashrrev_i32_e32 v241, 31, v240
	v_lshlrev_b64 v[240:241], 12, v[240:241]
	v_lshl_add_u64 v[240:241], s[10:11], 0, v[240:241]
	v_lshl_add_u64 v[242:243], v[240:241], 0, v[140:141]
	global_load_dwordx4 v[208:211], v[242:243], off
	global_load_dwordx4 v[212:215], v[242:243], off offset:256
	v_add_u32_e32 v240, 0x90, v142
	v_ashrrev_i32_e32 v241, 31, v240
	v_lshlrev_b64 v[240:241], 12, v[240:241]
	v_lshl_add_u64 v[240:241], s[10:11], 0, v[240:241]
	v_lshl_add_u64 v[242:243], v[240:241], 0, v[140:141]
	global_load_dwordx4 v[216:219], v[242:243], off
	global_load_dwordx4 v[220:223], v[242:243], off offset:256
	v_add_u32_e32 v240, 0xa0, v142
	v_ashrrev_i32_e32 v241, 31, v240
	v_lshlrev_b64 v[240:241], 12, v[240:241]
	v_lshl_add_u64 v[240:241], s[10:11], 0, v[240:241]
	v_lshl_add_u64 v[242:243], v[240:241], 0, v[140:141]
	global_load_dwordx4 v[224:227], v[242:243], off
	global_load_dwordx4 v[228:231], v[242:243], off offset:256
	v_add_u32_e32 v240, 0xb0, v142
	v_ashrrev_i32_e32 v241, 31, v240
	v_lshlrev_b64 v[240:241], 12, v[240:241]
	v_lshl_add_u64 v[240:241], s[10:11], 0, v[240:241]
	v_lshl_add_u64 v[242:243], v[240:241], 0, v[140:141]
	global_load_dwordx4 v[232:235], v[242:243], off
	global_load_dwordx4 v[236:239], v[242:243], off offset:256
	s_waitcnt vmcnt(0)
	v_lshl_add_u64 v[156:157], v[150:151], 0, v[140:141]
	v_mov_b32_e32 v150, v172
	v_mov_b32_e32 v151, v173
	v_mov_b32_e32 v152, v174
	v_mov_b32_e32 v153, v175
	v_cmp_gt_u32_e32 vcc, 16, v149
	v_lshlrev_b32_e32 v158, 16, v150
	v_and_b32_e32 v159, 0xffff0000, v150
	v_lshlrev_b32_e32 v150, 16, v151
	v_and_b32_e32 v151, 0xffff0000, v151
	v_lshlrev_b32_e32 v160, 16, v152
	v_and_b32_e32 v161, 0xffff0000, v152
	v_lshlrev_b32_e32 v152, 16, v153
	v_and_b32_e32 v153, 0xffff0000, v153
	v_pk_add_f32 v[162:163], v[126:127], v[150:151]
	v_pk_add_f32 v[158:159], v[124:125], v[158:159]
	v_pk_add_f32 v[164:165], v[122:123], v[152:153]
	v_pk_add_f32 v[160:161], v[120:121], v[160:161]
	v_cvt_pk_bf16_f32 v124, v158, v159
	v_cvt_pk_bf16_f32 v125, v162, v163
	v_mul_f32_e32 v143, v159, v159
	v_cvt_pk_bf16_f32 v126, v160, v161
	v_cvt_pk_bf16_f32 v127, v164, v165
	v_mov_b32_e32 v150, v176
	v_mov_b32_e32 v151, v177
	v_mov_b32_e32 v152, v178
	v_mov_b32_e32 v153, v179
	v_mul_f32_e32 v156, v163, v163
	v_mul_f32_e32 v157, v161, v161
	v_mul_f32_e32 v159, v165, v165
	v_fmac_f32_e32 v143, v158, v158
	v_fmac_f32_e32 v156, v162, v162
	v_fmac_f32_e32 v157, v160, v160
	v_fmac_f32_e32 v159, v164, v164
	v_add_f32_e32 v143, v143, v156
	v_add_f32_e32 v156, v157, v159
	v_add_f32_e32 v143, v143, v156
	v_and_b32_e32 v121, 64, v148
	v_xor_b32_e32 v120, 16, v148
	v_add_u32_e32 v121, 64, v121
	v_xor_b32_e32 v122, 32, v148
	v_cmp_lt_i32_e64 s[4:5], v120, v121
	v_lshlrev_b32_e32 v156, 16, v150
	v_and_b32_e32 v157, 0xffff0000, v150
	v_lshlrev_b32_e32 v150, 16, v151
	v_and_b32_e32 v151, 0xffff0000, v151
	v_lshlrev_b32_e32 v158, 16, v152
	v_and_b32_e32 v159, 0xffff0000, v152
	v_lshlrev_b32_e32 v152, 16, v153
	v_and_b32_e32 v153, 0xffff0000, v153
	v_pk_add_f32 v[118:119], v[118:119], v[150:151]
	v_pk_add_f32 v[116:117], v[116:117], v[156:157]
	v_pk_add_f32 v[150:151], v[114:115], v[152:153]
	v_pk_add_f32 v[152:153], v[112:113], v[158:159]
	v_mul_f32_e32 v112, v117, v117
	v_mul_f32_e32 v113, v119, v119
	v_mul_f32_e32 v114, v153, v153
	v_mul_f32_e32 v115, v151, v151
	v_fmac_f32_e32 v112, v116, v116
	v_fmac_f32_e32 v113, v118, v118
	v_fmac_f32_e32 v114, v152, v152
	v_fmac_f32_e32 v115, v150, v150
	v_add_f32_e32 v112, v112, v113
	v_add_f32_e32 v113, v114, v115
	v_cndmask_b32_e64 v120, v148, v120, s[4:5]
	v_cmp_lt_i32_e64 s[4:5], v122, v121
	v_add_f32_e32 v112, v112, v113
	v_add_f32_e32 v114, v143, v112
	v_cndmask_b32_e64 v123, v148, v122, s[4:5]
	v_lshlrev_b32_e32 v122, 2, v120
	ds_bpermute_b32 v115, v122, v114
	v_lshl_add_u64 v[112:113], s[12:13], 0, v[154:155]
	v_lshl_add_u64 v[154:155], v[112:113], 0, v[140:141]
	v_lshlrev_b32_e32 v112, 2, v123
	v_or_b32_e32 v121, s17, v166
	s_waitcnt lgkmcnt(0)
	v_add_f32_e32 v113, v114, v115
	ds_bpermute_b32 v114, v112, v113
	v_lshl_add_u32 v120, v121, 4, s65
	v_lshl_add_u32 v121, s19, 2, v120
	global_store_dwordx4 v[154:155], v[124:127], off
	v_cvt_pk_bf16_f32 v116, v116, v117
	v_cvt_pk_bf16_f32 v117, v118, v119
	v_cvt_pk_bf16_f32 v118, v152, v153
	v_cvt_pk_bf16_f32 v119, v150, v151
	global_store_dwordx4 v[154:155], v[116:119], off offset:256
	s_and_saveexec_b64 s[0:1], vcc
	s_cbranch_execz .LBB0_1655
	s_waitcnt lgkmcnt(0)
	v_add_f32_e32 v113, v113, v114
	ds_write_b32 v121, v113
; #define PG8_LAS __attribute__((address_space(3)))
; __device__ __forceinline__ float sq4(const f32x4 v) { return (v[0] * v[0] + v[1] * v[1]) + (v[2] * v[2] + v[3] * v[3]); }
; __device__ __forceinline__ u32x4 pack8(const f32x4 a, const f32x4 b) { u32x4 w; w.x = cvt_pk_bf16(a[0], a[1]); w.y = cvt_pk_bf16(a[2], a[3]); w.z = cvt_pk_bf16(b[0], b[1]); w.w = cvt_pk_bf16(b[2], b[3]); return w; }
;     __device__ __forceinline__ void operator()(const f32x4 (&acc)[2][2][4][2], const Unit& u, int wr_, int wc_, int fr_, int fq_) const {
;         int ln_; asm volatile("v_mbcnt_lo_u32_b32 %0, -1, 0\n\tv_mbcnt_hi_u32_b32 %0, -1, %0" : "=v"(ln_));
;         const int fr = ln_ & 15, fq = ln_ >> 4; (void)fr_; (void)fq_;
;         int wr = wr_, wc = wc_; asm volatile("" : "+s"(wr), "+s"(wc));
;         const int col0 = u.pn * BM + wc * 32 + 8 * fq;
;         PG8_LAS float* const xw = X + (wr * 64 + fr) * 4 + wc; const PG8_LAS float* const xr = X + (wr * 64 + fr) * 4;
; #pragma unroll
;         for (int ai = 0; ai < 2; ++ai)
; #pragma unroll
;             for (int m = 0; m < 4; ++m) {
;                 const int row = u.pm * BM + ai * HALF + wr * 64 + m * 16 + fr; const size_t off = (size_t)row * 1024 + col0;
;                 float s = 0.f;
; #pragma unroll
;                 for (int bj = 0; bj < 2; ++bj) {
;                     f32x4 b0, b1;
;                     const size_t boff = (size_t)row * base_ld + col0 + bj * HALF;
;                     if (BASE_BF16) unpack8(*(const u32x4*)((const bf16_t*)base + boff), b0, b1);
;                     else { b0 = *(const f32x4*)((const float*)base + boff); b1 = *(const f32x4*)((const float*)base + boff + 4); }
;                     const f32x4 h0 = b0 + acc[ai][bj][m][0] * ascale, h1 = b1 + acc[ai][bj][m][1] * ascale;
;                     st16_wt((hb + (size_t)row * hb_ld + col0 + bj * HALF), pack8(h0, h1));
;                     s += sq4(h0) + sq4(h1);
;                 }
;                 s += __shfl_xor(s, 16); s += __shfl_xor(s, 32);
;                 if (fq == 0) xw[(ai * HALF + m * 16) * 4] = s;
;             }
.LBB0_1655:
	s_or_b64 exec, exec, s[0:1]
	s_waitcnt lgkmcnt(0)
	v_or_b32_e32 v114, 16, v142
	v_ashrrev_i32_e32 v115, 31, v114
	v_lshlrev_b64 v[118:119], 12, v[114:115]
	v_lshl_add_u64 v[114:115], s[10:11], 0, v[118:119]
	v_lshl_add_u64 v[124:125], v[114:115], 0, v[140:141]
	v_mov_b32_e32 v114, v180
	v_mov_b32_e32 v115, v181
	v_mov_b32_e32 v116, v182
	v_mov_b32_e32 v117, v183
	v_lshlrev_b32_e32 v126, 16, v114
	v_and_b32_e32 v127, 0xffff0000, v114
	v_lshlrev_b32_e32 v114, 16, v115
	v_and_b32_e32 v115, 0xffff0000, v115
	v_lshlrev_b32_e32 v150, 16, v116
	v_and_b32_e32 v151, 0xffff0000, v116
	v_lshlrev_b32_e32 v116, 16, v117
	v_and_b32_e32 v117, 0xffff0000, v117
	v_pk_add_f32 v[114:115], v[110:111], v[114:115]
	v_pk_add_f32 v[126:127], v[108:109], v[126:127]
	v_pk_add_f32 v[116:117], v[106:107], v[116:117]
	v_pk_add_f32 v[150:151], v[104:105], v[150:151]
	v_cvt_pk_bf16_f32 v104, v126, v127
	v_cvt_pk_bf16_f32 v105, v114, v115
	v_mul_f32_e32 v113, v127, v127
	v_cvt_pk_bf16_f32 v106, v150, v151
	v_cvt_pk_bf16_f32 v107, v116, v117
	v_mov_b32_e32 v108, v188
	v_mov_b32_e32 v109, v189
	v_mov_b32_e32 v110, v190
	v_mov_b32_e32 v111, v191
	v_mul_f32_e32 v115, v115, v115
	v_mul_f32_e32 v123, v151, v151
	v_mul_f32_e32 v117, v117, v117
	v_fmac_f32_e32 v113, v126, v126
	v_fmac_f32_e32 v115, v114, v114
	v_fmac_f32_e32 v123, v150, v150
	v_fmac_f32_e32 v117, v116, v116
	v_add_f32_e32 v113, v113, v115
	v_add_f32_e32 v114, v123, v117
	v_add_f32_e32 v113, v113, v114
	v_lshlrev_b32_e32 v114, 16, v108
	v_and_b32_e32 v115, 0xffff0000, v108
	v_lshlrev_b32_e32 v108, 16, v109
	v_and_b32_e32 v109, 0xffff0000, v109
	v_lshlrev_b32_e32 v116, 16, v110
	v_and_b32_e32 v117, 0xffff0000, v110
	v_lshlrev_b32_e32 v110, 16, v111
	v_and_b32_e32 v111, 0xffff0000, v111
	v_pk_add_f32 v[102:103], v[102:103], v[108:109]
	v_pk_add_f32 v[100:101], v[100:101], v[114:115]
	v_pk_add_f32 v[108:109], v[98:99], v[110:111]
	v_pk_add_f32 v[110:111], v[96:97], v[116:117]
	v_mul_f32_e32 v96, v101, v101
	v_mul_f32_e32 v97, v103, v103
	v_mul_f32_e32 v98, v111, v111
	v_mul_f32_e32 v99, v109, v109
	v_fmac_f32_e32 v96, v100, v100
	v_fmac_f32_e32 v97, v102, v102
	v_fmac_f32_e32 v98, v110, v110
	v_fmac_f32_e32 v99, v108, v108
	v_add_f32_e32 v96, v96, v97
	v_add_f32_e32 v97, v98, v99
	v_add_f32_e32 v96, v96, v97
	v_add_f32_e32 v99, v113, v96
	ds_bpermute_b32 v113, v122, v99
	v_lshl_add_u64 v[96:97], s[12:13], 0, v[118:119]
	v_lshl_add_u64 v[114:115], v[96:97], 0, v[140:141]
	global_store_dwordx4 v[114:115], v[104:107], off
	v_cvt_pk_bf16_f32 v98, v100, v101
	s_waitcnt lgkmcnt(0)
	v_add_f32_e32 v96, v99, v113
	ds_bpermute_b32 v97, v112, v96
	v_cvt_pk_bf16_f32 v99, v102, v103
	v_cvt_pk_bf16_f32 v100, v110, v111
	v_cvt_pk_bf16_f32 v101, v108, v109
	global_store_dwordx4 v[114:115], v[98:101], off offset:256
	s_and_saveexec_b64 s[0:1], vcc
	s_cbranch_execz .LBB0_1657
	s_waitcnt lgkmcnt(0)
	v_add_f32_e32 v96, v96, v97
	ds_write_b32 v121, v96 offset:256
.LBB0_1657:
	s_or_b64 exec, exec, s[0:1]
	v_or_b32_e32 v96, 32, v142
	s_waitcnt lgkmcnt(0)
	v_ashrrev_i32_e32 v97, 31, v96
	v_lshlrev_b64 v[100:101], 12, v[96:97]
	v_lshl_add_u64 v[96:97], s[10:11], 0, v[100:101]
	v_lshl_add_u64 v[102:103], v[96:97], 0, v[140:141]
	v_mov_b32_e32 v96, v192
	v_mov_b32_e32 v97, v193
	v_mov_b32_e32 v98, v194
	v_mov_b32_e32 v99, v195
	v_lshlrev_b32_e32 v104, 16, v96
	v_and_b32_e32 v105, 0xffff0000, v96
	v_lshlrev_b32_e32 v96, 16, v97
	v_and_b32_e32 v97, 0xffff0000, v97
	v_lshlrev_b32_e32 v106, 16, v98
	v_and_b32_e32 v107, 0xffff0000, v98
	v_lshlrev_b32_e32 v98, 16, v99
	v_and_b32_e32 v99, 0xffff0000, v99
	v_pk_add_f32 v[96:97], v[94:95], v[96:97]
	v_pk_add_f32 v[104:105], v[92:93], v[104:105]
	v_pk_add_f32 v[98:99], v[90:91], v[98:99]
	v_pk_add_f32 v[106:107], v[88:89], v[106:107]
	v_cvt_pk_bf16_f32 v88, v104, v105
	v_cvt_pk_bf16_f32 v89, v96, v97
	v_mul_f32_e32 v97, v97, v97
	v_cvt_pk_bf16_f32 v90, v106, v107
	v_cvt_pk_bf16_f32 v91, v98, v99
	v_mov_b32_e32 v92, v196
	v_mov_b32_e32 v93, v197
	v_mov_b32_e32 v94, v198
	v_mov_b32_e32 v95, v199
	v_mul_f32_e32 v102, v105, v105
	v_mul_f32_e32 v103, v107, v107
	v_mul_f32_e32 v99, v99, v99
	v_fmac_f32_e32 v102, v104, v104
	v_fmac_f32_e32 v97, v96, v96
	v_fmac_f32_e32 v103, v106, v106
	v_fmac_f32_e32 v99, v98, v98
	v_add_f32_e32 v96, v102, v97
	v_add_f32_e32 v97, v103, v99
	v_add_f32_e32 v102, v96, v97
	v_lshlrev_b32_e32 v96, 16, v92
	v_and_b32_e32 v97, 0xffff0000, v92
	v_lshlrev_b32_e32 v92, 16, v93
	v_and_b32_e32 v93, 0xffff0000, v93
	v_lshlrev_b32_e32 v98, 16, v94
	v_and_b32_e32 v99, 0xffff0000, v94
	v_lshlrev_b32_e32 v94, 16, v95
	v_and_b32_e32 v95, 0xffff0000, v95
	v_pk_add_f32 v[86:87], v[86:87], v[92:93]
	v_pk_add_f32 v[84:85], v[84:85], v[96:97]
	v_pk_add_f32 v[92:93], v[82:83], v[94:95]
	v_pk_add_f32 v[94:95], v[80:81], v[98:99]
	v_mul_f32_e32 v80, v85, v85
	v_mul_f32_e32 v81, v87, v87
	v_mul_f32_e32 v82, v95, v95
	v_mul_f32_e32 v83, v93, v93
	v_fmac_f32_e32 v80, v84, v84
	v_fmac_f32_e32 v81, v86, v86
	v_fmac_f32_e32 v82, v94, v94
	v_fmac_f32_e32 v83, v92, v92
	v_add_f32_e32 v80, v80, v81
	v_add_f32_e32 v81, v82, v83
	v_add_f32_e32 v80, v80, v81
	v_add_f32_e32 v83, v102, v80
	ds_bpermute_b32 v98, v122, v83
	v_lshl_add_u64 v[80:81], s[12:13], 0, v[100:101]
	v_lshl_add_u64 v[96:97], v[80:81], 0, v[140:141]
	global_store_dwordx4 v[96:97], v[88:91], off
	v_cvt_pk_bf16_f32 v82, v84, v85
	s_waitcnt lgkmcnt(0)
	v_add_f32_e32 v80, v83, v98
	ds_bpermute_b32 v81, v112, v80
	v_cvt_pk_bf16_f32 v83, v86, v87
	v_cvt_pk_bf16_f32 v84, v94, v95
	v_cvt_pk_bf16_f32 v85, v92, v93
	global_store_dwordx4 v[96:97], v[82:85], off offset:256
	s_and_saveexec_b64 s[0:1], vcc
	s_cbranch_execz .LBB0_1659
	s_waitcnt lgkmcnt(0)
	v_add_f32_e32 v80, v80, v81
	ds_write_b32 v121, v80 offset:512
; #define PG8_LAS __attribute__((address_space(3)))
; __device__ __forceinline__ float sq4(const f32x4 v) { return (v[0] * v[0] + v[1] * v[1]) + (v[2] * v[2] + v[3] * v[3]); }
; __device__ __forceinline__ u32x4 pack8(const f32x4 a, const f32x4 b) { u32x4 w; w.x = cvt_pk_bf16(a[0], a[1]); w.y = cvt_pk_bf16(a[2], a[3]); w.z = cvt_pk_bf16(b[0], b[1]); w.w = cvt_pk_bf16(b[2], b[3]); return w; }
;     __device__ __forceinline__ void operator()(const f32x4 (&acc)[2][2][4][2], const Unit& u, int wr_, int wc_, int fr_, int fq_) const {
;         int ln_; asm volatile("v_mbcnt_lo_u32_b32 %0, -1, 0\n\tv_mbcnt_hi_u32_b32 %0, -1, %0" : "=v"(ln_));
;         const int fr = ln_ & 15, fq = ln_ >> 4; (void)fr_; (void)fq_;
;         int wr = wr_, wc = wc_; asm volatile("" : "+s"(wr), "+s"(wc));
;         const int col0 = u.pn * BM + wc * 32 + 8 * fq;
;         PG8_LAS float* const xw = X + (wr * 64 + fr) * 4 + wc; const PG8_LAS float* const xr = X + (wr * 64 + fr) * 4;
; #pragma unroll
;         for (int ai = 0; ai < 2; ++ai)
; #pragma unroll
;             for (int m = 0; m < 4; ++m) {
;                 const int row = u.pm * BM + ai * HALF + wr * 64 + m * 16 + fr; const size_t off = (size_t)row * 1024 + col0;
;                 float s = 0.f;
; #pragma unroll
;                 for (int bj = 0; bj < 2; ++bj) {
;                     f32x4 b0, b1;
;                     const size_t boff = (size_t)row * base_ld + col0 + bj * HALF;
;                     if (BASE_BF16) unpack8(*(const u32x4*)((const bf16_t*)base + boff), b0, b1);
;                     else { b0 = *(const f32x4*)((const float*)base + boff); b1 = *(const f32x4*)((const float*)base + boff + 4); }
;                     const f32x4 h0 = b0 + acc[ai][bj][m][0] * ascale, h1 = b1 + acc[ai][bj][m][1] * ascale;
;                     st16_wt((hb + (size_t)row * hb_ld + col0 + bj * HALF), pack8(h0, h1));
;                     s += sq4(h0) + sq4(h1);
;                 }
;                 s += __shfl_xor(s, 16); s += __shfl_xor(s, 32);
;                 if (fq == 0) xw[(ai * HALF + m * 16) * 4] = s;
;             }
.LBB0_1659:
	s_or_b64 exec, exec, s[0:1]
	v_or_b32_e32 v80, 48, v142
	s_waitcnt lgkmcnt(0)
	v_ashrrev_i32_e32 v81, 31, v80
	v_lshlrev_b64 v[84:85], 12, v[80:81]
	v_lshl_add_u64 v[80:81], s[10:11], 0, v[84:85]
	v_lshl_add_u64 v[86:87], v[80:81], 0, v[140:141]
	v_mov_b32_e32 v80, v200
	v_mov_b32_e32 v81, v201
	v_mov_b32_e32 v82, v202
	v_mov_b32_e32 v83, v203
	v_lshlrev_b32_e32 v88, 16, v80
	v_and_b32_e32 v89, 0xffff0000, v80
	v_lshlrev_b32_e32 v80, 16, v81
	v_and_b32_e32 v81, 0xffff0000, v81
	v_lshlrev_b32_e32 v90, 16, v82
	v_and_b32_e32 v91, 0xffff0000, v82
	v_lshlrev_b32_e32 v82, 16, v83
	v_and_b32_e32 v83, 0xffff0000, v83
	v_pk_add_f32 v[80:81], v[78:79], v[80:81]
	v_pk_add_f32 v[88:89], v[76:77], v[88:89]
	v_pk_add_f32 v[82:83], v[74:75], v[82:83]
	v_pk_add_f32 v[90:91], v[72:73], v[90:91]
	v_cvt_pk_bf16_f32 v72, v88, v89
	v_cvt_pk_bf16_f32 v73, v80, v81
	v_mul_f32_e32 v81, v81, v81
	v_cvt_pk_bf16_f32 v74, v90, v91
	v_cvt_pk_bf16_f32 v75, v82, v83
	v_mov_b32_e32 v76, v204
	v_mov_b32_e32 v77, v205
	v_mov_b32_e32 v78, v206
	v_mov_b32_e32 v79, v207
	v_mul_f32_e32 v86, v89, v89
	v_mul_f32_e32 v87, v91, v91
	v_mul_f32_e32 v83, v83, v83
	v_fmac_f32_e32 v86, v88, v88
	v_fmac_f32_e32 v81, v80, v80
	v_fmac_f32_e32 v87, v90, v90
	v_fmac_f32_e32 v83, v82, v82
	v_add_f32_e32 v80, v86, v81
	v_add_f32_e32 v81, v87, v83
	v_add_f32_e32 v86, v80, v81
	v_lshlrev_b32_e32 v80, 16, v76
	v_and_b32_e32 v81, 0xffff0000, v76
	v_lshlrev_b32_e32 v76, 16, v77
	v_and_b32_e32 v77, 0xffff0000, v77
	v_lshlrev_b32_e32 v82, 16, v78
	v_and_b32_e32 v83, 0xffff0000, v78
	v_lshlrev_b32_e32 v78, 16, v79
	v_and_b32_e32 v79, 0xffff0000, v79
	v_pk_add_f32 v[70:71], v[70:71], v[76:77]
	v_pk_add_f32 v[68:69], v[68:69], v[80:81]
	v_pk_add_f32 v[76:77], v[66:67], v[78:79]
	v_pk_add_f32 v[78:79], v[64:65], v[82:83]
	v_mul_f32_e32 v64, v69, v69
	v_mul_f32_e32 v65, v71, v71
	v_mul_f32_e32 v66, v79, v79
	v_mul_f32_e32 v67, v77, v77
	v_fmac_f32_e32 v64, v68, v68
	v_fmac_f32_e32 v65, v70, v70
	v_fmac_f32_e32 v66, v78, v78
	v_fmac_f32_e32 v67, v76, v76
	v_add_f32_e32 v64, v64, v65
	v_add_f32_e32 v65, v66, v67
	v_add_f32_e32 v64, v64, v65
	v_add_f32_e32 v67, v86, v64
	ds_bpermute_b32 v82, v122, v67
	v_lshl_add_u64 v[64:65], s[12:13], 0, v[84:85]
	v_lshl_add_u64 v[80:81], v[64:65], 0, v[140:141]
	global_store_dwordx4 v[80:81], v[72:75], off
	v_cvt_pk_bf16_f32 v66, v68, v69
	s_waitcnt lgkmcnt(0)
	v_add_f32_e32 v64, v67, v82
	ds_bpermute_b32 v65, v112, v64
	v_cvt_pk_bf16_f32 v67, v70, v71
	v_cvt_pk_bf16_f32 v68, v78, v79
	v_cvt_pk_bf16_f32 v69, v76, v77
	global_store_dwordx4 v[80:81], v[66:69], off offset:256
	s_and_saveexec_b64 s[0:1], vcc
	s_cbranch_execz .LBB0_1661
	s_waitcnt lgkmcnt(0)
	v_add_f32_e32 v64, v64, v65
	ds_write_b32 v121, v64 offset:768
.LBB0_1661:
	s_or_b64 exec, exec, s[0:1]
	v_add_u32_e32 v64, 0x80, v142
	s_waitcnt lgkmcnt(0)
	v_ashrrev_i32_e32 v65, 31, v64
	v_lshlrev_b64 v[68:69], 12, v[64:65]
	v_lshl_add_u64 v[64:65], s[10:11], 0, v[68:69]
	v_lshl_add_u64 v[70:71], v[64:65], 0, v[140:141]
	v_mov_b32_e32 v64, v208
	v_mov_b32_e32 v65, v209
	v_mov_b32_e32 v66, v210
	v_mov_b32_e32 v67, v211
	v_lshlrev_b32_e32 v72, 16, v64
	v_and_b32_e32 v73, 0xffff0000, v64
	v_lshlrev_b32_e32 v64, 16, v65
	v_and_b32_e32 v65, 0xffff0000, v65
	v_lshlrev_b32_e32 v74, 16, v66
	v_and_b32_e32 v75, 0xffff0000, v66
	v_lshlrev_b32_e32 v66, 16, v67
	v_and_b32_e32 v67, 0xffff0000, v67
	v_pk_add_f32 v[64:65], v[62:63], v[64:65]
	v_pk_add_f32 v[72:73], v[60:61], v[72:73]
	v_pk_add_f32 v[66:67], v[58:59], v[66:67]
	v_pk_add_f32 v[74:75], v[56:57], v[74:75]
	v_cvt_pk_bf16_f32 v56, v72, v73
	v_cvt_pk_bf16_f32 v57, v64, v65
	v_mul_f32_e32 v65, v65, v65
	v_cvt_pk_bf16_f32 v58, v74, v75
	v_cvt_pk_bf16_f32 v59, v66, v67
	v_mov_b32_e32 v60, v212
	v_mov_b32_e32 v61, v213
	v_mov_b32_e32 v62, v214
	v_mov_b32_e32 v63, v215
	v_mul_f32_e32 v70, v73, v73
	v_mul_f32_e32 v71, v75, v75
	v_mul_f32_e32 v67, v67, v67
	v_fmac_f32_e32 v70, v72, v72
	v_fmac_f32_e32 v65, v64, v64
	v_fmac_f32_e32 v71, v74, v74
	v_fmac_f32_e32 v67, v66, v66
	v_add_f32_e32 v64, v70, v65
	v_add_f32_e32 v65, v71, v67
	v_add_f32_e32 v70, v64, v65
	v_lshlrev_b32_e32 v64, 16, v60
	v_and_b32_e32 v65, 0xffff0000, v60
	v_lshlrev_b32_e32 v60, 16, v61
	v_and_b32_e32 v61, 0xffff0000, v61
	v_lshlrev_b32_e32 v66, 16, v62
	v_and_b32_e32 v67, 0xffff0000, v62
	v_lshlrev_b32_e32 v62, 16, v63
	v_and_b32_e32 v63, 0xffff0000, v63
	v_pk_add_f32 v[54:55], v[54:55], v[60:61]
	v_pk_add_f32 v[52:53], v[52:53], v[64:65]
	v_pk_add_f32 v[60:61], v[50:51], v[62:63]
	v_pk_add_f32 v[62:63], v[48:49], v[66:67]
	v_mul_f32_e32 v48, v53, v53
	v_mul_f32_e32 v49, v55, v55
	v_mul_f32_e32 v50, v63, v63
	v_mul_f32_e32 v51, v61, v61
	v_fmac_f32_e32 v48, v52, v52
	v_fmac_f32_e32 v49, v54, v54
	v_fmac_f32_e32 v50, v62, v62
	v_fmac_f32_e32 v51, v60, v60
	v_add_f32_e32 v48, v48, v49
	v_add_f32_e32 v49, v50, v51
	v_add_f32_e32 v48, v48, v49
	v_add_f32_e32 v51, v70, v48
	ds_bpermute_b32 v66, v122, v51
	v_lshl_add_u64 v[48:49], s[12:13], 0, v[68:69]
	v_lshl_add_u64 v[64:65], v[48:49], 0, v[140:141]
	global_store_dwordx4 v[64:65], v[56:59], off
	v_cvt_pk_bf16_f32 v50, v52, v53
	s_waitcnt lgkmcnt(0)
	v_add_f32_e32 v48, v51, v66
	ds_bpermute_b32 v49, v112, v48
	v_cvt_pk_bf16_f32 v51, v54, v55
	v_cvt_pk_bf16_f32 v52, v62, v63
	v_cvt_pk_bf16_f32 v53, v60, v61
	global_store_dwordx4 v[64:65], v[50:53], off offset:256
	s_and_saveexec_b64 s[0:1], vcc
	s_cbranch_execz .LBB0_1663
	s_waitcnt lgkmcnt(0)
	v_add_f32_e32 v48, v48, v49
	ds_write_b32 v121, v48 offset:2048
; #define PG8_LAS __attribute__((address_space(3)))
; __device__ __forceinline__ float sq4(const f32x4 v) { return (v[0] * v[0] + v[1] * v[1]) + (v[2] * v[2] + v[3] * v[3]); }
; __device__ __forceinline__ u32x4 pack8(const f32x4 a, const f32x4 b) { u32x4 w; w.x = cvt_pk_bf16(a[0], a[1]); w.y = cvt_pk_bf16(a[2], a[3]); w.z = cvt_pk_bf16(b[0], b[1]); w.w = cvt_pk_bf16(b[2], b[3]); return w; }
;     __device__ __forceinline__ void operator()(const f32x4 (&acc)[2][2][4][2], const Unit& u, int wr_, int wc_, int fr_, int fq_) const {
;         int ln_; asm volatile("v_mbcnt_lo_u32_b32 %0, -1, 0\n\tv_mbcnt_hi_u32_b32 %0, -1, %0" : "=v"(ln_));
;         const int fr = ln_ & 15, fq = ln_ >> 4; (void)fr_; (void)fq_;
;         int wr = wr_, wc = wc_; asm volatile("" : "+s"(wr), "+s"(wc));
;         const int col0 = u.pn * BM + wc * 32 + 8 * fq;
;         PG8_LAS float* const xw = X + (wr * 64 + fr) * 4 + wc; const PG8_LAS float* const xr = X + (wr * 64 + fr) * 4;
; #pragma unroll
;         for (int ai = 0; ai < 2; ++ai)
; #pragma unroll
;             for (int m = 0; m < 4; ++m) {
;                 const int row = u.pm * BM + ai * HALF + wr * 64 + m * 16 + fr; const size_t off = (size_t)row * 1024 + col0;
;                 float s = 0.f;
; #pragma unroll
;                 for (int bj = 0; bj < 2; ++bj) {
;                     f32x4 b0, b1;
;                     const size_t boff = (size_t)row * base_ld + col0 + bj * HALF;
;                     if (BASE_BF16) unpack8(*(const u32x4*)((const bf16_t*)base + boff), b0, b1);
;                     else { b0 = *(const f32x4*)((const float*)base + boff); b1 = *(const f32x4*)((const float*)base + boff + 4); }
;                     const f32x4 h0 = b0 + acc[ai][bj][m][0] * ascale, h1 = b1 + acc[ai][bj][m][1] * ascale;
;                     st16_wt((hb + (size_t)row * hb_ld + col0 + bj * HALF), pack8(h0, h1));
;                     s += sq4(h0) + sq4(h1);
;                 }
;                 s += __shfl_xor(s, 16); s += __shfl_xor(s, 32);
;                 if (fq == 0) xw[(ai * HALF + m * 16) * 4] = s;
;             }
.LBB0_1663:
	s_or_b64 exec, exec, s[0:1]
	v_add_u32_e32 v48, 0x90, v142
	s_waitcnt lgkmcnt(0)
	v_ashrrev_i32_e32 v49, 31, v48
	v_lshlrev_b64 v[52:53], 12, v[48:49]
	v_lshl_add_u64 v[48:49], s[10:11], 0, v[52:53]
	v_lshl_add_u64 v[54:55], v[48:49], 0, v[140:141]
	v_mov_b32_e32 v48, v216
	v_mov_b32_e32 v49, v217
	v_mov_b32_e32 v50, v218
	v_mov_b32_e32 v51, v219
	v_lshlrev_b32_e32 v56, 16, v48
	v_and_b32_e32 v57, 0xffff0000, v48
	v_lshlrev_b32_e32 v48, 16, v49
	v_and_b32_e32 v49, 0xffff0000, v49
	v_lshlrev_b32_e32 v58, 16, v50
	v_and_b32_e32 v59, 0xffff0000, v50
	v_lshlrev_b32_e32 v50, 16, v51
	v_and_b32_e32 v51, 0xffff0000, v51
	v_pk_add_f32 v[48:49], v[46:47], v[48:49]
	v_pk_add_f32 v[56:57], v[44:45], v[56:57]
	v_pk_add_f32 v[50:51], v[42:43], v[50:51]
	v_pk_add_f32 v[58:59], v[40:41], v[58:59]
	v_cvt_pk_bf16_f32 v40, v56, v57
	v_cvt_pk_bf16_f32 v41, v48, v49
	v_mul_f32_e32 v49, v49, v49
	v_cvt_pk_bf16_f32 v42, v58, v59
	v_cvt_pk_bf16_f32 v43, v50, v51
	v_mov_b32_e32 v44, v220
	v_mov_b32_e32 v45, v221
	v_mov_b32_e32 v46, v222
	v_mov_b32_e32 v47, v223
	v_mul_f32_e32 v54, v57, v57
	v_mul_f32_e32 v55, v59, v59
	v_mul_f32_e32 v51, v51, v51
	v_fmac_f32_e32 v54, v56, v56
	v_fmac_f32_e32 v49, v48, v48
	v_fmac_f32_e32 v55, v58, v58
	v_fmac_f32_e32 v51, v50, v50
	v_add_f32_e32 v48, v54, v49
	v_add_f32_e32 v49, v55, v51
	v_add_f32_e32 v54, v48, v49
	v_lshlrev_b32_e32 v48, 16, v44
	v_and_b32_e32 v49, 0xffff0000, v44
	v_lshlrev_b32_e32 v44, 16, v45
	v_and_b32_e32 v45, 0xffff0000, v45
	v_lshlrev_b32_e32 v50, 16, v46
	v_and_b32_e32 v51, 0xffff0000, v46
	v_lshlrev_b32_e32 v46, 16, v47
	v_and_b32_e32 v47, 0xffff0000, v47
	v_pk_add_f32 v[38:39], v[38:39], v[44:45]
	v_pk_add_f32 v[36:37], v[36:37], v[48:49]
	v_pk_add_f32 v[44:45], v[34:35], v[46:47]
	v_pk_add_f32 v[46:47], v[32:33], v[50:51]
	v_mul_f32_e32 v32, v37, v37
	v_mul_f32_e32 v33, v39, v39
	v_mul_f32_e32 v34, v47, v47
	v_mul_f32_e32 v35, v45, v45
	v_fmac_f32_e32 v32, v36, v36
	v_fmac_f32_e32 v33, v38, v38
	v_fmac_f32_e32 v34, v46, v46
	v_fmac_f32_e32 v35, v44, v44
	v_add_f32_e32 v32, v32, v33
	v_add_f32_e32 v33, v34, v35
	v_add_f32_e32 v32, v32, v33
	v_add_f32_e32 v35, v54, v32
	ds_bpermute_b32 v50, v122, v35
	v_lshl_add_u64 v[32:33], s[12:13], 0, v[52:53]
	v_lshl_add_u64 v[48:49], v[32:33], 0, v[140:141]
	global_store_dwordx4 v[48:49], v[40:43], off
	v_cvt_pk_bf16_f32 v34, v36, v37
	s_waitcnt lgkmcnt(0)
	v_add_f32_e32 v32, v35, v50
	ds_bpermute_b32 v33, v112, v32
	v_cvt_pk_bf16_f32 v35, v38, v39
	v_cvt_pk_bf16_f32 v36, v46, v47
	v_cvt_pk_bf16_f32 v37, v44, v45
	global_store_dwordx4 v[48:49], v[34:37], off offset:256
	s_and_saveexec_b64 s[0:1], vcc
	s_cbranch_execz .LBB0_1665
	s_waitcnt lgkmcnt(0)
	v_add_f32_e32 v32, v32, v33
	ds_write_b32 v121, v32 offset:2304
; #define PG8_LAS __attribute__((address_space(3)))
; __device__ __forceinline__ float sq4(const f32x4 v) { return (v[0] * v[0] + v[1] * v[1]) + (v[2] * v[2] + v[3] * v[3]); }
; __device__ __forceinline__ u32x4 pack8(const f32x4 a, const f32x4 b) { u32x4 w; w.x = cvt_pk_bf16(a[0], a[1]); w.y = cvt_pk_bf16(a[2], a[3]); w.z = cvt_pk_bf16(b[0], b[1]); w.w = cvt_pk_bf16(b[2], b[3]); return w; }
;     __device__ __forceinline__ void operator()(const f32x4 (&acc)[2][2][4][2], const Unit& u, int wr_, int wc_, int fr_, int fq_) const {
;         int ln_; asm volatile("v_mbcnt_lo_u32_b32 %0, -1, 0\n\tv_mbcnt_hi_u32_b32 %0, -1, %0" : "=v"(ln_));
;         const int fr = ln_ & 15, fq = ln_ >> 4; (void)fr_; (void)fq_;
;         int wr = wr_, wc = wc_; asm volatile("" : "+s"(wr), "+s"(wc));
;         const int col0 = u.pn * BM + wc * 32 + 8 * fq;
;         PG8_LAS float* const xw = X + (wr * 64 + fr) * 4 + wc; const PG8_LAS float* const xr = X + (wr * 64 + fr) * 4;
; #pragma unroll
;         for (int ai = 0; ai < 2; ++ai)
; #pragma unroll
;             for (int m = 0; m < 4; ++m) {
;                 const int row = u.pm * BM + ai * HALF + wr * 64 + m * 16 + fr; const size_t off = (size_t)row * 1024 + col0;
;                 float s = 0.f;
; #pragma unroll
;                 for (int bj = 0; bj < 2; ++bj) {
;                     f32x4 b0, b1;
;                     const size_t boff = (size_t)row * base_ld + col0 + bj * HALF;
;                     if (BASE_BF16) unpack8(*(const u32x4*)((const bf16_t*)base + boff), b0, b1);
;                     else { b0 = *(const f32x4*)((const float*)base + boff); b1 = *(const f32x4*)((const float*)base + boff + 4); }
;                     const f32x4 h0 = b0 + acc[ai][bj][m][0] * ascale, h1 = b1 + acc[ai][bj][m][1] * ascale;
;                     st16_wt((hb + (size_t)row * hb_ld + col0 + bj * HALF), pack8(h0, h1));
;                     s += sq4(h0) + sq4(h1);
;                 }
;                 s += __shfl_xor(s, 16); s += __shfl_xor(s, 32);
;                 if (fq == 0) xw[(ai * HALF + m * 16) * 4] = s;
;             }
.LBB0_1665:
	s_or_b64 exec, exec, s[0:1]
	v_add_u32_e32 v32, 0xa0, v142
	s_waitcnt lgkmcnt(0)
	v_ashrrev_i32_e32 v33, 31, v32
	v_lshlrev_b64 v[36:37], 12, v[32:33]
	v_lshl_add_u64 v[32:33], s[10:11], 0, v[36:37]
	v_lshl_add_u64 v[38:39], v[32:33], 0, v[140:141]
	v_mov_b32_e32 v32, v224
	v_mov_b32_e32 v33, v225
	v_mov_b32_e32 v34, v226
	v_mov_b32_e32 v35, v227
	v_lshlrev_b32_e32 v40, 16, v32
	v_and_b32_e32 v41, 0xffff0000, v32
	v_lshlrev_b32_e32 v32, 16, v33
	v_and_b32_e32 v33, 0xffff0000, v33
	v_lshlrev_b32_e32 v42, 16, v34
	v_and_b32_e32 v43, 0xffff0000, v34
	v_lshlrev_b32_e32 v34, 16, v35
	v_and_b32_e32 v35, 0xffff0000, v35
	v_pk_add_f32 v[32:33], v[30:31], v[32:33]
	v_pk_add_f32 v[40:41], v[28:29], v[40:41]
	v_pk_add_f32 v[34:35], v[26:27], v[34:35]
	v_pk_add_f32 v[42:43], v[24:25], v[42:43]
	v_cvt_pk_bf16_f32 v24, v40, v41
	v_cvt_pk_bf16_f32 v25, v32, v33
	v_mul_f32_e32 v33, v33, v33
	v_cvt_pk_bf16_f32 v26, v42, v43
	v_cvt_pk_bf16_f32 v27, v34, v35
	v_mov_b32_e32 v28, v228
	v_mov_b32_e32 v29, v229
	v_mov_b32_e32 v30, v230
	v_mov_b32_e32 v31, v231
	v_mul_f32_e32 v38, v41, v41
	v_mul_f32_e32 v39, v43, v43
	v_mul_f32_e32 v35, v35, v35
	v_fmac_f32_e32 v38, v40, v40
	v_fmac_f32_e32 v33, v32, v32
	v_fmac_f32_e32 v39, v42, v42
	v_fmac_f32_e32 v35, v34, v34
	v_add_f32_e32 v32, v38, v33
	v_add_f32_e32 v33, v39, v35
	v_add_f32_e32 v38, v32, v33
	v_lshlrev_b32_e32 v32, 16, v28
	v_and_b32_e32 v33, 0xffff0000, v28
	v_lshlrev_b32_e32 v28, 16, v29
	v_and_b32_e32 v29, 0xffff0000, v29
	v_lshlrev_b32_e32 v34, 16, v30
	v_and_b32_e32 v35, 0xffff0000, v30
	v_lshlrev_b32_e32 v30, 16, v31
	v_and_b32_e32 v31, 0xffff0000, v31
	v_pk_add_f32 v[22:23], v[22:23], v[28:29]
	v_pk_add_f32 v[20:21], v[20:21], v[32:33]
	v_pk_add_f32 v[28:29], v[18:19], v[30:31]
	v_pk_add_f32 v[30:31], v[16:17], v[34:35]
	v_mul_f32_e32 v16, v21, v21
	v_mul_f32_e32 v17, v23, v23
	v_mul_f32_e32 v18, v31, v31
	v_mul_f32_e32 v19, v29, v29
	v_fmac_f32_e32 v16, v20, v20
	v_fmac_f32_e32 v17, v22, v22
	v_fmac_f32_e32 v18, v30, v30
	v_fmac_f32_e32 v19, v28, v28
	v_add_f32_e32 v16, v16, v17
	v_add_f32_e32 v17, v18, v19
	v_add_f32_e32 v16, v16, v17
	v_add_f32_e32 v19, v38, v16
	ds_bpermute_b32 v34, v122, v19
	v_lshl_add_u64 v[16:17], s[12:13], 0, v[36:37]
	v_lshl_add_u64 v[32:33], v[16:17], 0, v[140:141]
	global_store_dwordx4 v[32:33], v[24:27], off
	v_cvt_pk_bf16_f32 v18, v20, v21
	s_waitcnt lgkmcnt(0)
	v_add_f32_e32 v16, v19, v34
	ds_bpermute_b32 v17, v112, v16
	v_cvt_pk_bf16_f32 v19, v22, v23
	v_cvt_pk_bf16_f32 v20, v30, v31
	v_cvt_pk_bf16_f32 v21, v28, v29
	global_store_dwordx4 v[32:33], v[18:21], off offset:256
	s_and_saveexec_b64 s[0:1], vcc
	s_cbranch_execz .LBB0_1667
	s_waitcnt lgkmcnt(0)
	v_add_f32_e32 v16, v16, v17
	ds_write_b32 v121, v16 offset:2560
.LBB0_1667:
	s_or_b64 exec, exec, s[0:1]
	v_add_u32_e32 v16, 0xb0, v142
	s_waitcnt lgkmcnt(0)
	v_ashrrev_i32_e32 v17, 31, v16
	v_lshlrev_b64 v[20:21], 12, v[16:17]
	v_lshl_add_u64 v[16:17], s[10:11], 0, v[20:21]
	v_lshl_add_u64 v[22:23], v[16:17], 0, v[140:141]
	v_mov_b32_e32 v16, v232
	v_mov_b32_e32 v17, v233
	v_mov_b32_e32 v18, v234
	v_mov_b32_e32 v19, v235
	v_lshlrev_b32_e32 v24, 16, v16
	v_and_b32_e32 v25, 0xffff0000, v16
	v_lshlrev_b32_e32 v16, 16, v17
	v_and_b32_e32 v17, 0xffff0000, v17
	v_lshlrev_b32_e32 v26, 16, v18
	v_and_b32_e32 v27, 0xffff0000, v18
	v_lshlrev_b32_e32 v18, 16, v19
	v_and_b32_e32 v19, 0xffff0000, v19
	v_pk_add_f32 v[16:17], v[14:15], v[16:17]
	v_pk_add_f32 v[24:25], v[12:13], v[24:25]
	v_pk_add_f32 v[18:19], v[10:11], v[18:19]
	v_pk_add_f32 v[26:27], v[8:9], v[26:27]
	v_cvt_pk_bf16_f32 v8, v24, v25
	v_cvt_pk_bf16_f32 v9, v16, v17
	v_mul_f32_e32 v17, v17, v17
	v_cvt_pk_bf16_f32 v10, v26, v27
	v_cvt_pk_bf16_f32 v11, v18, v19
	v_mov_b32_e32 v12, v236
	v_mov_b32_e32 v13, v237
	v_mov_b32_e32 v14, v238
	v_mov_b32_e32 v15, v239
	v_mul_f32_e32 v22, v25, v25
	v_mul_f32_e32 v23, v27, v27
	v_mul_f32_e32 v19, v19, v19
	v_fmac_f32_e32 v22, v24, v24
	v_fmac_f32_e32 v17, v16, v16
	v_fmac_f32_e32 v23, v26, v26
	v_fmac_f32_e32 v19, v18, v18
	v_add_f32_e32 v16, v22, v17
	v_add_f32_e32 v17, v23, v19
	v_add_f32_e32 v22, v16, v17
	v_lshlrev_b32_e32 v16, 16, v12
	v_and_b32_e32 v17, 0xffff0000, v12
	v_lshlrev_b32_e32 v12, 16, v13
	v_and_b32_e32 v13, 0xffff0000, v13
	v_lshlrev_b32_e32 v18, 16, v14
	v_and_b32_e32 v19, 0xffff0000, v14
	v_lshlrev_b32_e32 v14, 16, v15
	v_and_b32_e32 v15, 0xffff0000, v15
	v_pk_add_f32 v[6:7], v[6:7], v[12:13]
	v_pk_add_f32 v[4:5], v[4:5], v[16:17]
	v_pk_add_f32 v[12:13], v[2:3], v[14:15]
	v_pk_add_f32 v[14:15], v[0:1], v[18:19]
	v_mul_f32_e32 v0, v5, v5
	v_mul_f32_e32 v1, v7, v7
	v_mul_f32_e32 v2, v15, v15
	v_mul_f32_e32 v3, v13, v13
	v_fmac_f32_e32 v0, v4, v4
	v_fmac_f32_e32 v1, v6, v6
	v_fmac_f32_e32 v2, v14, v14
	v_fmac_f32_e32 v3, v12, v12
	v_add_f32_e32 v0, v0, v1
	v_add_f32_e32 v1, v2, v3
	v_add_f32_e32 v0, v0, v1
	v_add_f32_e32 v3, v22, v0
	ds_bpermute_b32 v18, v122, v3
	v_lshl_add_u64 v[0:1], s[12:13], 0, v[20:21]
	v_lshl_add_u64 v[16:17], v[0:1], 0, v[140:141]
	global_store_dwordx4 v[16:17], v[8:11], off
	v_cvt_pk_bf16_f32 v2, v4, v5
	s_waitcnt lgkmcnt(0)
	v_add_f32_e32 v0, v3, v18
	ds_bpermute_b32 v1, v112, v0
	v_cvt_pk_bf16_f32 v3, v6, v7
	v_cvt_pk_bf16_f32 v4, v14, v15
	v_cvt_pk_bf16_f32 v5, v12, v13
	global_store_dwordx4 v[16:17], v[2:5], off offset:256
	s_and_saveexec_b64 s[0:1], vcc
	s_cbranch_execz .LBB0_1669
	s_waitcnt lgkmcnt(0)
	v_add_f32_e32 v0, v0, v1
	ds_write_b32 v121, v0 offset:2816

; #define PG8_LAS __attribute__((address_space(3)))
; __device__ __forceinline__ float sq4(const f32x4 v) { return (v[0] * v[0] + v[1] * v[1]) + (v[2] * v[2] + v[3] * v[3]); }
; __device__ __forceinline__ u32x4 pack8(const f32x4 a, const f32x4 b) { u32x4 w; w.x = cvt_pk_bf16(a[0], a[1]); w.y = cvt_pk_bf16(a[2], a[3]); w.z = cvt_pk_bf16(b[0], b[1]); w.w = cvt_pk_bf16(b[2], b[3]); return w; }
;     __device__ __forceinline__ void operator()(const f32x4 (&acc)[2][2][4][2], const Unit& u, int wr_, int wc_, int fr_, int fq_) const {
;         int ln_; asm volatile("v_mbcnt_lo_u32_b32 %0, -1, 0\n\tv_mbcnt_hi_u32_b32 %0, -1, %0" : "=v"(ln_));
;         const int fr = ln_ & 15, fq = ln_ >> 4; (void)fr_; (void)fq_;
;         int wr = wr_, wc = wc_; asm volatile("" : "+s"(wr), "+s"(wc));
;         const int col0 = u.pn * BM + wc * 32 + 8 * fq;
;         PG8_LAS float* const xw = X + (wr * 64 + fr) * 4 + wc; const PG8_LAS float* const xr = X + (wr * 64 + fr) * 4;
; #pragma unroll
;         for (int ai = 0; ai < 2; ++ai)
; #pragma unroll
;             for (int m = 0; m < 4; ++m) {
;                 const int row = u.pm * BM + ai * HALF + wr * 64 + m * 16 + fr; const size_t off = (size_t)row * 1024 + col0;
;                 float s = 0.f;
; #pragma unroll
;                 for (int bj = 0; bj < 2; ++bj) {
;                     f32x4 b0, b1;
;                     const size_t boff = (size_t)row * base_ld + col0 + bj * HALF;
;                     if (BASE_BF16) unpack8(*(const u32x4*)((const bf16_t*)base + boff), b0, b1);
;                     else { b0 = *(const f32x4*)((const float*)base + boff); b1 = *(const f32x4*)((const float*)base + boff + 4); }
;                     const f32x4 h0 = b0 + acc[ai][bj][m][0] * ascale, h1 = b1 + acc[ai][bj][m][1] * ascale;
;                     st16_wt((hb + (size_t)row * hb_ld + col0 + bj * HALF), pack8(h0, h1));
;                     s += sq4(h0) + sq4(h1);
;                 }
;                 s += __shfl_xor(s, 16); s += __shfl_xor(s, 32);
;                 if (fq == 0) xw[(ai * HALF + m * 16) * 4] = s;
;             }
.LBB0_1970:
	v_mbcnt_lo_u32_b32 v24, -1, 0
	v_mbcnt_hi_u32_b32 v24, -1, v24
	s_mov_b32 s0, s53
	v_and_b32_e32 v25, 15, v24
	s_mov_b32 s23, s62
	s_lshl_b32 s7, s7, 8
	s_lshl_b32 s1, s6, 8
	s_lshl_b32 s4, s23, 5
	v_ashrrev_i32_e32 v16, 1, v24
	s_lshl_b32 s21, s0, 6
	v_or_b32_e32 v17, s7, v25
	v_and_b32_e32 v16, -8, v16
	s_add_i32 s4, s4, s1
	v_add_u32_e32 v18, s21, v17
	v_add_u32_e32 v16, s4, v16
	v_ashrrev_i32_e32 v19, 31, v18
	v_ashrrev_i32_e32 v17, 31, v16
	v_lshlrev_b64 v[26:27], 12, v[18:19]
	v_lshl_add_u64 v[26:27], s[10:11], 0, v[26:27]
	v_lshlrev_b64 v[16:17], 1, v[16:17]
	v_mov_b32_e32 v236, v18
	v_ashrrev_i32_e32 v237, 31, v236
	v_lshlrev_b64 v[236:237], 12, v[236:237]
	v_lshl_add_u64 v[236:237], s[10:11], 0, v[236:237]
	v_lshl_add_u64 v[238:239], v[236:237], 0, v[16:17]
	global_load_dwordx4 v[164:167], v[238:239], off
	global_load_dwordx4 v[172:175], v[238:239], off offset:256
	v_or_b32_e32 v236, 16, v18
	v_ashrrev_i32_e32 v237, 31, v236
	v_lshlrev_b64 v[236:237], 12, v[236:237]
	v_lshl_add_u64 v[236:237], s[10:11], 0, v[236:237]
	v_lshl_add_u64 v[238:239], v[236:237], 0, v[16:17]
	global_load_dwordx4 v[176:179], v[238:239], off
	global_load_dwordx4 v[180:183], v[238:239], off offset:256
	v_or_b32_e32 v236, 32, v18
	v_ashrrev_i32_e32 v237, 31, v236
	v_lshlrev_b64 v[236:237], 12, v[236:237]
	v_lshl_add_u64 v[236:237], s[10:11], 0, v[236:237]
	v_lshl_add_u64 v[238:239], v[236:237], 0, v[16:17]
	global_load_dwordx4 v[188:191], v[238:239], off
	global_load_dwordx4 v[192:195], v[238:239], off offset:256
	v_or_b32_e32 v236, 48, v18
	v_ashrrev_i32_e32 v237, 31, v236
	v_lshlrev_b64 v[236:237], 12, v[236:237]
	v_lshl_add_u64 v[236:237], s[10:11], 0, v[236:237]
	v_lshl_add_u64 v[238:239], v[236:237], 0, v[16:17]
	global_load_dwordx4 v[196:199], v[238:239], off
	global_load_dwordx4 v[200:203], v[238:239], off offset:256
	v_add_u32_e32 v236, 0x80, v18
	v_ashrrev_i32_e32 v237, 31, v236
	v_lshlrev_b64 v[236:237], 12, v[236:237]
	v_lshl_add_u64 v[236:237], s[10:11], 0, v[236:237]
	v_lshl_add_u64 v[238:239], v[236:237], 0, v[16:17]
	global_load_dwordx4 v[204:207], v[238:239], off
	global_load_dwordx4 v[208:211], v[238:239], off offset:256
	v_add_u32_e32 v236, 0x90, v18
	v_ashrrev_i32_e32 v237, 31, v236
	v_lshlrev_b64 v[236:237], 12, v[236:237]
	v_lshl_add_u64 v[236:237], s[10:11], 0, v[236:237]
	v_lshl_add_u64 v[238:239], v[236:237], 0, v[16:17]
	global_load_dwordx4 v[212:215], v[238:239], off
	global_load_dwordx4 v[216:219], v[238:239], off offset:256
	v_add_u32_e32 v236, 0xa0, v18
	v_ashrrev_i32_e32 v237, 31, v236
	v_lshlrev_b64 v[236:237], 12, v[236:237]
	v_lshl_add_u64 v[236:237], s[10:11], 0, v[236:237]
	v_lshl_add_u64 v[238:239], v[236:237], 0, v[16:17]
	global_load_dwordx4 v[220:223], v[238:239], off
	global_load_dwordx4 v[224:227], v[238:239], off offset:256
	v_add_u32_e32 v236, 0xb0, v18
	v_ashrrev_i32_e32 v237, 31, v236
	v_lshlrev_b64 v[236:237], 12, v[236:237]
	v_lshl_add_u64 v[236:237], s[10:11], 0, v[236:237]
	v_lshl_add_u64 v[238:239], v[236:237], 0, v[16:17]
	global_load_dwordx4 v[228:231], v[238:239], off
	global_load_dwordx4 v[232:235], v[238:239], off offset:256
	s_waitcnt vmcnt(0)
	v_lshl_add_u64 v[26:27], v[26:27], 0, v[16:17]
	v_mov_b32_e32 v40, v164
	v_mov_b32_e32 v41, v165
	v_mov_b32_e32 v42, v166
	v_mov_b32_e32 v43, v167
	v_lshlrev_b64 v[158:159], 11, v[18:19]
	v_xor_b32_e32 v157, 32, v156
	v_or_b32_e32 v25, s21, v25
	v_lshl_add_u32 v25, v25, 4, s70
	v_cmp_gt_u32_e32 vcc, 16, v24
	v_lshlrev_b32_e32 v136, 16, v40
	v_and_b32_e32 v137, 0xffff0000, v40
	v_lshlrev_b32_e32 v40, 16, v41
	v_and_b32_e32 v41, 0xffff0000, v41
	v_lshlrev_b32_e32 v138, 16, v42
	v_and_b32_e32 v139, 0xffff0000, v42
	v_lshlrev_b32_e32 v42, 16, v43
	v_and_b32_e32 v43, 0xffff0000, v43
	v_pk_add_f32 v[146:147], v[146:147], v[40:41]
	v_pk_add_f32 v[150:151], v[150:151], v[136:137]
	v_pk_add_f32 v[148:149], v[148:149], v[42:43]
	v_pk_add_f32 v[144:145], v[144:145], v[138:139]
	v_cvt_pk_bf16_f32 v40, v150, v151
	v_cvt_pk_bf16_f32 v41, v146, v147
	v_mul_f32_e32 v19, v151, v151
	v_cvt_pk_bf16_f32 v42, v144, v145
	v_cvt_pk_bf16_f32 v43, v148, v149
	v_mov_b32_e32 v136, v172
	v_mov_b32_e32 v137, v173
	v_mov_b32_e32 v138, v174
	v_mov_b32_e32 v139, v175
	v_mul_f32_e32 v147, v147, v147
	v_mul_f32_e32 v145, v145, v145
	v_mul_f32_e32 v149, v149, v149
	v_fmac_f32_e32 v19, v150, v150
	v_fmac_f32_e32 v147, v146, v146
	v_fmac_f32_e32 v145, v144, v144
	v_fmac_f32_e32 v149, v148, v148
	v_add_f32_e32 v19, v19, v147
	v_add_f32_e32 v144, v145, v149
	v_add_f32_e32 v19, v19, v144
	v_and_b32_e32 v27, 64, v156
	v_xor_b32_e32 v26, 16, v156
	v_add_u32_e32 v27, 64, v27
	v_cmp_lt_i32_e64 s[4:5], v26, v27
	v_lshlrev_b32_e32 v144, 16, v136
	v_and_b32_e32 v145, 0xffff0000, v136
	v_lshlrev_b32_e32 v136, 16, v137
	v_and_b32_e32 v137, 0xffff0000, v137
	v_lshlrev_b32_e32 v146, 16, v138
	v_and_b32_e32 v147, 0xffff0000, v138
	v_lshlrev_b32_e32 v138, 16, v139
	v_and_b32_e32 v139, 0xffff0000, v139
	v_pk_add_f32 v[136:137], v[124:125], v[136:137]
	v_pk_add_f32 v[124:125], v[126:127], v[144:145]
	v_pk_add_f32 v[138:139], v[140:141], v[138:139]
	v_pk_add_f32 v[126:127], v[142:143], v[146:147]
	v_mul_f32_e32 v140, v125, v125
	v_mul_f32_e32 v141, v137, v137
	v_mul_f32_e32 v142, v127, v127
	v_mul_f32_e32 v143, v139, v139
	v_fmac_f32_e32 v140, v124, v124
	v_fmac_f32_e32 v141, v136, v136
	v_fmac_f32_e32 v142, v126, v126
	v_fmac_f32_e32 v143, v138, v138
	v_add_f32_e32 v140, v140, v141
	v_add_f32_e32 v141, v142, v143
	v_cndmask_b32_e64 v26, v156, v26, s[4:5]
	v_add_f32_e32 v140, v140, v141
	v_cmp_lt_i32_e64 s[4:5], v157, v27
	v_lshlrev_b32_e32 v27, 2, v26
	v_add_f32_e32 v19, v19, v140
	ds_bpermute_b32 v142, v27, v19
	v_lshl_add_u64 v[140:141], s[12:13], 0, v[158:159]
	v_cndmask_b32_e64 v157, v156, v157, s[4:5]
	v_lshl_add_u64 v[140:141], v[140:141], 0, v[16:17]
	global_store_dwordx4 v[140:141], v[40:43], off
	v_lshl_add_u32 v26, s23, 2, v25
	v_cvt_pk_bf16_f32 v124, v124, v125
	v_cvt_pk_bf16_f32 v125, v136, v137
	v_cvt_pk_bf16_f32 v126, v126, v127
	v_cvt_pk_bf16_f32 v127, v138, v139
	s_waitcnt lgkmcnt(0)
	v_add_f32_e32 v40, v19, v142
	v_lshlrev_b32_e32 v19, 2, v157
	ds_bpermute_b32 v41, v19, v40
	global_store_dwordx4 v[140:141], v[124:127], off offset:256
	s_and_saveexec_b64 s[0:1], vcc
	s_cbranch_execz .LBB0_1972
	s_waitcnt lgkmcnt(0)
	v_add_f32_e32 v40, v40, v41
	ds_write_b32 v26, v40
; #define PG8_LAS __attribute__((address_space(3)))
; __device__ __forceinline__ float sq4(const f32x4 v) { return (v[0] * v[0] + v[1] * v[1]) + (v[2] * v[2] + v[3] * v[3]); }
; __device__ __forceinline__ u32x4 pack8(const f32x4 a, const f32x4 b) { u32x4 w; w.x = cvt_pk_bf16(a[0], a[1]); w.y = cvt_pk_bf16(a[2], a[3]); w.z = cvt_pk_bf16(b[0], b[1]); w.w = cvt_pk_bf16(b[2], b[3]); return w; }
;     __device__ __forceinline__ void operator()(const f32x4 (&acc)[2][2][4][2], const Unit& u, int wr_, int wc_, int fr_, int fq_) const {
;         int ln_; asm volatile("v_mbcnt_lo_u32_b32 %0, -1, 0\n\tv_mbcnt_hi_u32_b32 %0, -1, %0" : "=v"(ln_));
;         const int fr = ln_ & 15, fq = ln_ >> 4; (void)fr_; (void)fq_;
;         int wr = wr_, wc = wc_; asm volatile("" : "+s"(wr), "+s"(wc));
;         const int col0 = u.pn * BM + wc * 32 + 8 * fq;
;         PG8_LAS float* const xw = X + (wr * 64 + fr) * 4 + wc; const PG8_LAS float* const xr = X + (wr * 64 + fr) * 4;
; #pragma unroll
;         for (int ai = 0; ai < 2; ++ai)
; #pragma unroll
;             for (int m = 0; m < 4; ++m) {
;                 const int row = u.pm * BM + ai * HALF + wr * 64 + m * 16 + fr; const size_t off = (size_t)row * 1024 + col0;
;                 float s = 0.f;
; #pragma unroll
;                 for (int bj = 0; bj < 2; ++bj) {
;                     f32x4 b0, b1;
;                     const size_t boff = (size_t)row * base_ld + col0 + bj * HALF;
;                     if (BASE_BF16) unpack8(*(const u32x4*)((const bf16_t*)base + boff), b0, b1);
;                     else { b0 = *(const f32x4*)((const float*)base + boff); b1 = *(const f32x4*)((const float*)base + boff + 4); }
;                     const f32x4 h0 = b0 + acc[ai][bj][m][0] * ascale, h1 = b1 + acc[ai][bj][m][1] * ascale;
;                     st16_wt((hb + (size_t)row * hb_ld + col0 + bj * HALF), pack8(h0, h1));
;                     s += sq4(h0) + sq4(h1);
;                 }
;                 s += __shfl_xor(s, 16); s += __shfl_xor(s, 32);
;                 if (fq == 0) xw[(ai * HALF + m * 16) * 4] = s;
;             }
.LBB0_1972:
	s_or_b64 exec, exec, s[0:1]
	v_or_b32_e32 v124, 16, v18
	v_ashrrev_i32_e32 v125, 31, v124
	s_waitcnt lgkmcnt(0)
	v_lshlrev_b64 v[40:41], 12, v[124:125]
	v_lshl_add_u64 v[40:41], s[10:11], 0, v[40:41]
	v_lshl_add_u64 v[126:127], v[40:41], 0, v[16:17]
	v_mov_b32_e32 v40, v176
	v_mov_b32_e32 v41, v177
	v_mov_b32_e32 v42, v178
	v_mov_b32_e32 v43, v179
	v_lshlrev_b64 v[124:125], 11, v[124:125]
	v_lshlrev_b32_e32 v136, 16, v40
	v_and_b32_e32 v137, 0xffff0000, v40
	v_lshlrev_b32_e32 v40, 16, v41
	v_and_b32_e32 v41, 0xffff0000, v41
	v_lshlrev_b32_e32 v138, 16, v42
	v_and_b32_e32 v139, 0xffff0000, v42
	v_lshlrev_b32_e32 v42, 16, v43
	v_and_b32_e32 v43, 0xffff0000, v43
	v_pk_add_f32 v[122:123], v[122:123], v[40:41]
	v_pk_add_f32 v[120:121], v[120:121], v[136:137]
	v_pk_add_f32 v[136:137], v[118:119], v[42:43]
	v_pk_add_f32 v[138:139], v[116:117], v[138:139]
	v_cvt_pk_bf16_f32 v40, v120, v121
	v_cvt_pk_bf16_f32 v41, v122, v123
	v_mul_f32_e32 v121, v121, v121
	v_cvt_pk_bf16_f32 v42, v138, v139
	v_cvt_pk_bf16_f32 v43, v136, v137
	v_mov_b32_e32 v116, v180
	v_mov_b32_e32 v117, v181
	v_mov_b32_e32 v118, v182
	v_mov_b32_e32 v119, v183
	v_mul_f32_e32 v123, v123, v123
	v_mul_f32_e32 v126, v139, v139
	v_mul_f32_e32 v127, v137, v137
	v_fmac_f32_e32 v121, v120, v120
	v_fmac_f32_e32 v123, v122, v122
	v_fmac_f32_e32 v126, v138, v138
	v_fmac_f32_e32 v127, v136, v136
	v_add_f32_e32 v120, v121, v123
	v_add_f32_e32 v121, v126, v127
	v_add_f32_e32 v126, v120, v121
	v_lshlrev_b32_e32 v120, 16, v116
	v_and_b32_e32 v121, 0xffff0000, v116
	v_lshlrev_b32_e32 v116, 16, v117
	v_and_b32_e32 v117, 0xffff0000, v117
	v_lshlrev_b32_e32 v122, 16, v118
	v_and_b32_e32 v123, 0xffff0000, v118
	v_lshlrev_b32_e32 v118, 16, v119
	v_and_b32_e32 v119, 0xffff0000, v119
	v_pk_add_f32 v[114:115], v[114:115], v[116:117]
	v_pk_add_f32 v[112:113], v[112:113], v[120:121]
	v_pk_add_f32 v[116:117], v[110:111], v[118:119]
	v_pk_add_f32 v[110:111], v[108:109], v[122:123]
	v_mul_f32_e32 v108, v113, v113
	v_mul_f32_e32 v109, v115, v115
	v_mul_f32_e32 v118, v111, v111
	v_mul_f32_e32 v119, v117, v117
	v_fmac_f32_e32 v108, v112, v112
	v_fmac_f32_e32 v109, v114, v114
	v_fmac_f32_e32 v118, v110, v110
	v_fmac_f32_e32 v119, v116, v116
	v_add_f32_e32 v108, v108, v109
	v_add_f32_e32 v109, v118, v119
	v_add_f32_e32 v108, v108, v109
	v_add_f32_e32 v120, v126, v108
	ds_bpermute_b32 v121, v27, v120
	v_lshl_add_u64 v[108:109], s[12:13], 0, v[124:125]
	v_lshl_add_u64 v[118:119], v[108:109], 0, v[16:17]
	global_store_dwordx4 v[118:119], v[40:43], off
	v_cvt_pk_bf16_f32 v108, v112, v113
	v_cvt_pk_bf16_f32 v109, v114, v115
	v_cvt_pk_bf16_f32 v110, v110, v111
	v_cvt_pk_bf16_f32 v111, v116, v117
	global_store_dwordx4 v[118:119], v[108:111], off offset:256
	s_waitcnt lgkmcnt(0)
	v_add_f32_e32 v40, v120, v121
	ds_bpermute_b32 v41, v19, v40
	s_and_saveexec_b64 s[0:1], vcc
	s_cbranch_execz .LBB0_1974
	s_waitcnt lgkmcnt(0)
	v_add_f32_e32 v40, v40, v41
	ds_write_b32 v26, v40 offset:256
.LBB0_1974:
	s_or_b64 exec, exec, s[0:1]
	v_or_b32_e32 v108, 32, v18
	v_ashrrev_i32_e32 v109, 31, v108
	s_waitcnt lgkmcnt(0)
	v_lshlrev_b64 v[40:41], 12, v[108:109]
	v_lshl_add_u64 v[40:41], s[10:11], 0, v[40:41]
	v_lshl_add_u64 v[110:111], v[40:41], 0, v[16:17]
	v_mov_b32_e32 v40, v188
	v_mov_b32_e32 v41, v189
	v_mov_b32_e32 v42, v190
	v_mov_b32_e32 v43, v191
	v_lshlrev_b64 v[108:109], 11, v[108:109]
	v_lshlrev_b32_e32 v112, 16, v40
	v_and_b32_e32 v113, 0xffff0000, v40
	v_lshlrev_b32_e32 v40, 16, v41
	v_and_b32_e32 v41, 0xffff0000, v41
	v_lshlrev_b32_e32 v114, 16, v42
	v_and_b32_e32 v115, 0xffff0000, v42
	v_lshlrev_b32_e32 v42, 16, v43
	v_and_b32_e32 v43, 0xffff0000, v43
	v_pk_add_f32 v[106:107], v[106:107], v[40:41]
	v_pk_add_f32 v[104:105], v[104:105], v[112:113]
	v_pk_add_f32 v[112:113], v[102:103], v[42:43]
	v_pk_add_f32 v[114:115], v[100:101], v[114:115]
	v_cvt_pk_bf16_f32 v40, v104, v105
	v_cvt_pk_bf16_f32 v41, v106, v107
	v_mul_f32_e32 v105, v105, v105
	v_cvt_pk_bf16_f32 v42, v114, v115
	v_cvt_pk_bf16_f32 v43, v112, v113
	v_mov_b32_e32 v100, v192
	v_mov_b32_e32 v101, v193
	v_mov_b32_e32 v102, v194
	v_mov_b32_e32 v103, v195
	v_mul_f32_e32 v107, v107, v107
	v_mul_f32_e32 v110, v115, v115
	v_mul_f32_e32 v111, v113, v113
	v_fmac_f32_e32 v105, v104, v104
	v_fmac_f32_e32 v107, v106, v106
	v_fmac_f32_e32 v110, v114, v114
	v_fmac_f32_e32 v111, v112, v112
	v_add_f32_e32 v104, v105, v107
	v_add_f32_e32 v105, v110, v111
	v_add_f32_e32 v110, v104, v105
	v_lshlrev_b32_e32 v104, 16, v100
	v_and_b32_e32 v105, 0xffff0000, v100
	v_lshlrev_b32_e32 v100, 16, v101
	v_and_b32_e32 v101, 0xffff0000, v101
	v_lshlrev_b32_e32 v106, 16, v102
	v_and_b32_e32 v107, 0xffff0000, v102
	v_lshlrev_b32_e32 v102, 16, v103
	v_and_b32_e32 v103, 0xffff0000, v103
	v_pk_add_f32 v[98:99], v[98:99], v[100:101]
	v_pk_add_f32 v[96:97], v[96:97], v[104:105]
	v_pk_add_f32 v[100:101], v[94:95], v[102:103]
	v_pk_add_f32 v[94:95], v[92:93], v[106:107]
	v_mul_f32_e32 v92, v97, v97
	v_mul_f32_e32 v93, v99, v99
	v_mul_f32_e32 v102, v95, v95
	v_mul_f32_e32 v103, v101, v101
	v_fmac_f32_e32 v92, v96, v96
	v_fmac_f32_e32 v93, v98, v98
	v_fmac_f32_e32 v102, v94, v94
	v_fmac_f32_e32 v103, v100, v100
	v_add_f32_e32 v92, v92, v93
	v_add_f32_e32 v93, v102, v103
	v_add_f32_e32 v92, v92, v93
	v_add_f32_e32 v104, v110, v92
	ds_bpermute_b32 v105, v27, v104
	v_lshl_add_u64 v[92:93], s[12:13], 0, v[108:109]
	v_lshl_add_u64 v[102:103], v[92:93], 0, v[16:17]
	global_store_dwordx4 v[102:103], v[40:43], off
	v_cvt_pk_bf16_f32 v92, v96, v97
	v_cvt_pk_bf16_f32 v93, v98, v99
	v_cvt_pk_bf16_f32 v94, v94, v95
	v_cvt_pk_bf16_f32 v95, v100, v101
	global_store_dwordx4 v[102:103], v[92:95], off offset:256
	s_waitcnt lgkmcnt(0)
	v_add_f32_e32 v40, v104, v105
	ds_bpermute_b32 v41, v19, v40
	s_and_saveexec_b64 s[0:1], vcc
	s_cbranch_execz .LBB0_1976
	s_waitcnt lgkmcnt(0)
	v_add_f32_e32 v40, v40, v41
	ds_write_b32 v26, v40 offset:512
; __device__ __forceinline__ float sq4(const f32x4 v) { return (v[0] * v[0] + v[1] * v[1]) + (v[2] * v[2] + v[3] * v[3]); }
; __device__ __forceinline__ u32x4 pack8(const f32x4 a, const f32x4 b) { u32x4 w; w.x = cvt_pk_bf16(a[0], a[1]); w.y = cvt_pk_bf16(a[2], a[3]); w.z = cvt_pk_bf16(b[0], b[1]); w.w = cvt_pk_bf16(b[2], b[3]); return w; }
;     __device__ __forceinline__ void operator()(const f32x4 (&acc)[2][2][4][2], const Unit& u, int wr_, int wc_, int fr_, int fq_) const {
;     ...
; #pragma unroll
;         for (int ai = 0; ai < 2; ++ai)
; #pragma unroll
;             for (int m = 0; m < 4; ++m) {
;                 const int row = u.pm * BM + ai * HALF + wr * 64 + m * 16 + fr; const size_t off = (size_t)row * 1024 + col0;
;                 float s = 0.f;
; #pragma unroll
;                 for (int bj = 0; bj < 2; ++bj) {
;                     f32x4 b0, b1;
;                     const size_t boff = (size_t)row * base_ld + col0 + bj * HALF;
;                     if (BASE_BF16) unpack8(*(const u32x4*)((const bf16_t*)base + boff), b0, b1);
;                     else { b0 = *(const f32x4*)((const float*)base + boff); b1 = *(const f32x4*)((const float*)base + boff + 4); }
;                     const f32x4 h0 = b0 + acc[ai][bj][m][0] * ascale, h1 = b1 + acc[ai][bj][m][1] * ascale;
;                     st16_wt((hb + (size_t)row * hb_ld + col0 + bj * HALF), pack8(h0, h1));
;                     s += sq4(h0) + sq4(h1);
;                 }
;                 s += __shfl_xor(s, 16); s += __shfl_xor(s, 32);
;                 if (fq == 0) xw[(ai * HALF + m * 16) * 4] = s;
;             }
.LBB0_1976:
	s_or_b64 exec, exec, s[0:1]
	v_or_b32_e32 v92, 48, v18
	v_ashrrev_i32_e32 v93, 31, v92
	s_waitcnt lgkmcnt(0)
	v_lshlrev_b64 v[40:41], 12, v[92:93]
	v_lshl_add_u64 v[40:41], s[10:11], 0, v[40:41]
	v_lshl_add_u64 v[94:95], v[40:41], 0, v[16:17]
	v_mov_b32_e32 v40, v196
	v_mov_b32_e32 v41, v197
	v_mov_b32_e32 v42, v198
	v_mov_b32_e32 v43, v199
	v_lshlrev_b64 v[92:93], 11, v[92:93]
	v_lshlrev_b32_e32 v96, 16, v40
	v_and_b32_e32 v97, 0xffff0000, v40
	v_lshlrev_b32_e32 v40, 16, v41
	v_and_b32_e32 v41, 0xffff0000, v41
	v_lshlrev_b32_e32 v98, 16, v42
	v_and_b32_e32 v99, 0xffff0000, v42
	v_lshlrev_b32_e32 v42, 16, v43
	v_and_b32_e32 v43, 0xffff0000, v43
	v_pk_add_f32 v[90:91], v[90:91], v[40:41]
	v_pk_add_f32 v[88:89], v[88:89], v[96:97]
	v_pk_add_f32 v[96:97], v[86:87], v[42:43]
	v_pk_add_f32 v[98:99], v[84:85], v[98:99]
	v_cvt_pk_bf16_f32 v40, v88, v89
	v_cvt_pk_bf16_f32 v41, v90, v91
	v_mul_f32_e32 v89, v89, v89
	v_cvt_pk_bf16_f32 v42, v98, v99
	v_cvt_pk_bf16_f32 v43, v96, v97
	v_mov_b32_e32 v84, v200
	v_mov_b32_e32 v85, v201
	v_mov_b32_e32 v86, v202
	v_mov_b32_e32 v87, v203
	v_mul_f32_e32 v91, v91, v91
	v_mul_f32_e32 v94, v99, v99
	v_mul_f32_e32 v95, v97, v97
	v_fmac_f32_e32 v89, v88, v88
	v_fmac_f32_e32 v91, v90, v90
	v_fmac_f32_e32 v94, v98, v98
	v_fmac_f32_e32 v95, v96, v96
	v_add_f32_e32 v88, v89, v91
	v_add_f32_e32 v89, v94, v95
	v_add_f32_e32 v94, v88, v89
	v_lshlrev_b32_e32 v88, 16, v84
	v_and_b32_e32 v89, 0xffff0000, v84
	v_lshlrev_b32_e32 v84, 16, v85
	v_and_b32_e32 v85, 0xffff0000, v85
	v_lshlrev_b32_e32 v90, 16, v86
	v_and_b32_e32 v91, 0xffff0000, v86
	v_lshlrev_b32_e32 v86, 16, v87
	v_and_b32_e32 v87, 0xffff0000, v87
	v_pk_add_f32 v[82:83], v[82:83], v[84:85]
	v_pk_add_f32 v[80:81], v[80:81], v[88:89]
	v_pk_add_f32 v[84:85], v[78:79], v[86:87]
	v_pk_add_f32 v[78:79], v[76:77], v[90:91]
	v_mul_f32_e32 v76, v81, v81
	v_mul_f32_e32 v77, v83, v83
	v_mul_f32_e32 v86, v79, v79
	v_mul_f32_e32 v87, v85, v85
	v_fmac_f32_e32 v76, v80, v80
	v_fmac_f32_e32 v77, v82, v82
	v_fmac_f32_e32 v86, v78, v78
	v_fmac_f32_e32 v87, v84, v84
	v_add_f32_e32 v76, v76, v77
	v_add_f32_e32 v77, v86, v87
	v_add_f32_e32 v76, v76, v77
	v_add_f32_e32 v88, v94, v76
	ds_bpermute_b32 v89, v27, v88
	v_lshl_add_u64 v[76:77], s[12:13], 0, v[92:93]
	v_lshl_add_u64 v[86:87], v[76:77], 0, v[16:17]
	global_store_dwordx4 v[86:87], v[40:43], off
	v_cvt_pk_bf16_f32 v76, v80, v81
	v_cvt_pk_bf16_f32 v77, v82, v83
	v_cvt_pk_bf16_f32 v78, v78, v79
	v_cvt_pk_bf16_f32 v79, v84, v85
	global_store_dwordx4 v[86:87], v[76:79], off offset:256
	s_waitcnt lgkmcnt(0)
	v_add_f32_e32 v40, v88, v89
	ds_bpermute_b32 v41, v19, v40
	s_and_saveexec_b64 s[0:1], vcc
	s_cbranch_execz .LBB0_1978
	s_waitcnt lgkmcnt(0)
	v_add_f32_e32 v40, v40, v41
	ds_write_b32 v26, v40 offset:768
.LBB0_1978:
	s_or_b64 exec, exec, s[0:1]
	v_add_u32_e32 v76, 0x80, v18
	v_ashrrev_i32_e32 v77, 31, v76
	s_waitcnt lgkmcnt(0)
	v_lshlrev_b64 v[40:41], 12, v[76:77]
	v_lshl_add_u64 v[40:41], s[10:11], 0, v[40:41]
	v_lshl_add_u64 v[78:79], v[40:41], 0, v[16:17]
	v_mov_b32_e32 v40, v204
	v_mov_b32_e32 v41, v205
	v_mov_b32_e32 v42, v206
	v_mov_b32_e32 v43, v207
	v_lshlrev_b64 v[76:77], 11, v[76:77]
	v_lshlrev_b32_e32 v80, 16, v40
	v_and_b32_e32 v81, 0xffff0000, v40
	v_lshlrev_b32_e32 v40, 16, v41
	v_and_b32_e32 v41, 0xffff0000, v41
	v_lshlrev_b32_e32 v82, 16, v42
	v_and_b32_e32 v83, 0xffff0000, v42
	v_lshlrev_b32_e32 v42, 16, v43
	v_and_b32_e32 v43, 0xffff0000, v43
	v_pk_add_f32 v[74:75], v[74:75], v[40:41]
	v_pk_add_f32 v[72:73], v[72:73], v[80:81]
	v_pk_add_f32 v[80:81], v[70:71], v[42:43]
	v_pk_add_f32 v[82:83], v[68:69], v[82:83]
	v_cvt_pk_bf16_f32 v40, v72, v73
	v_cvt_pk_bf16_f32 v41, v74, v75
	v_mul_f32_e32 v73, v73, v73
	v_cvt_pk_bf16_f32 v42, v82, v83
	v_cvt_pk_bf16_f32 v43, v80, v81
	v_mov_b32_e32 v68, v208
	v_mov_b32_e32 v69, v209
	v_mov_b32_e32 v70, v210
	v_mov_b32_e32 v71, v211
	v_mul_f32_e32 v75, v75, v75
	v_mul_f32_e32 v78, v83, v83
	v_mul_f32_e32 v79, v81, v81
	v_fmac_f32_e32 v73, v72, v72
	v_fmac_f32_e32 v75, v74, v74
	v_fmac_f32_e32 v78, v82, v82
	v_fmac_f32_e32 v79, v80, v80
	v_add_f32_e32 v72, v73, v75
	v_add_f32_e32 v73, v78, v79
	v_add_f32_e32 v78, v72, v73
	v_lshlrev_b32_e32 v72, 16, v68
	v_and_b32_e32 v73, 0xffff0000, v68
	v_lshlrev_b32_e32 v68, 16, v69
	v_and_b32_e32 v69, 0xffff0000, v69
	v_lshlrev_b32_e32 v74, 16, v70
	v_and_b32_e32 v75, 0xffff0000, v70
	v_lshlrev_b32_e32 v70, 16, v71
	v_and_b32_e32 v71, 0xffff0000, v71
	v_pk_add_f32 v[66:67], v[66:67], v[68:69]
	v_pk_add_f32 v[64:65], v[64:65], v[72:73]
	v_pk_add_f32 v[68:69], v[62:63], v[70:71]
	v_pk_add_f32 v[62:63], v[60:61], v[74:75]
	v_mul_f32_e32 v60, v65, v65
	v_mul_f32_e32 v61, v67, v67
	v_mul_f32_e32 v70, v63, v63
	v_mul_f32_e32 v71, v69, v69
	v_fmac_f32_e32 v60, v64, v64
	v_fmac_f32_e32 v61, v66, v66
	v_fmac_f32_e32 v70, v62, v62
	v_fmac_f32_e32 v71, v68, v68
	v_add_f32_e32 v60, v60, v61
	v_add_f32_e32 v61, v70, v71
	v_add_f32_e32 v60, v60, v61
	v_add_f32_e32 v72, v78, v60
	ds_bpermute_b32 v73, v27, v72
	v_lshl_add_u64 v[60:61], s[12:13], 0, v[76:77]
	v_lshl_add_u64 v[70:71], v[60:61], 0, v[16:17]
	global_store_dwordx4 v[70:71], v[40:43], off
	v_cvt_pk_bf16_f32 v60, v64, v65
	v_cvt_pk_bf16_f32 v61, v66, v67
	v_cvt_pk_bf16_f32 v62, v62, v63
	v_cvt_pk_bf16_f32 v63, v68, v69
	global_store_dwordx4 v[70:71], v[60:63], off offset:256
	s_waitcnt lgkmcnt(0)
	v_add_f32_e32 v40, v72, v73
	ds_bpermute_b32 v41, v19, v40
	s_and_saveexec_b64 s[0:1], vcc
	s_cbranch_execz .LBB0_1980
	s_waitcnt lgkmcnt(0)
	v_add_f32_e32 v40, v40, v41
	ds_write_b32 v26, v40 offset:2048
; __device__ __forceinline__ float sq4(const f32x4 v) { return (v[0] * v[0] + v[1] * v[1]) + (v[2] * v[2] + v[3] * v[3]); }
; __device__ __forceinline__ u32x4 pack8(const f32x4 a, const f32x4 b) { u32x4 w; w.x = cvt_pk_bf16(a[0], a[1]); w.y = cvt_pk_bf16(a[2], a[3]); w.z = cvt_pk_bf16(b[0], b[1]); w.w = cvt_pk_bf16(b[2], b[3]); return w; }
;     __device__ __forceinline__ void operator()(const f32x4 (&acc)[2][2][4][2], const Unit& u, int wr_, int wc_, int fr_, int fq_) const {
;     ...
; #pragma unroll
;         for (int ai = 0; ai < 2; ++ai)
; #pragma unroll
;             for (int m = 0; m < 4; ++m) {
;                 const int row = u.pm * BM + ai * HALF + wr * 64 + m * 16 + fr; const size_t off = (size_t)row * 1024 + col0;
;                 float s = 0.f;
; #pragma unroll
;                 for (int bj = 0; bj < 2; ++bj) {
;                     f32x4 b0, b1;
;                     const size_t boff = (size_t)row * base_ld + col0 + bj * HALF;
;                     if (BASE_BF16) unpack8(*(const u32x4*)((const bf16_t*)base + boff), b0, b1);
;                     else { b0 = *(const f32x4*)((const float*)base + boff); b1 = *(const f32x4*)((const float*)base + boff + 4); }
;                     const f32x4 h0 = b0 + acc[ai][bj][m][0] * ascale, h1 = b1 + acc[ai][bj][m][1] * ascale;
;                     st16_wt((hb + (size_t)row * hb_ld + col0 + bj * HALF), pack8(h0, h1));
;                     s += sq4(h0) + sq4(h1);
;                 }
;                 s += __shfl_xor(s, 16); s += __shfl_xor(s, 32);
;                 if (fq == 0) xw[(ai * HALF + m * 16) * 4] = s;
;             }
.LBB0_1980:
	s_or_b64 exec, exec, s[0:1]
	v_add_u32_e32 v60, 0x90, v18
	v_ashrrev_i32_e32 v61, 31, v60
	s_waitcnt lgkmcnt(0)
	v_lshlrev_b64 v[40:41], 12, v[60:61]
	v_lshl_add_u64 v[40:41], s[10:11], 0, v[40:41]
	v_lshl_add_u64 v[62:63], v[40:41], 0, v[16:17]
	v_mov_b32_e32 v40, v212
	v_mov_b32_e32 v41, v213
	v_mov_b32_e32 v42, v214
	v_mov_b32_e32 v43, v215
	v_lshlrev_b64 v[60:61], 11, v[60:61]
	v_lshlrev_b32_e32 v64, 16, v40
	v_and_b32_e32 v65, 0xffff0000, v40
	v_lshlrev_b32_e32 v40, 16, v41
	v_and_b32_e32 v41, 0xffff0000, v41
	v_lshlrev_b32_e32 v66, 16, v42
	v_and_b32_e32 v67, 0xffff0000, v42
	v_lshlrev_b32_e32 v42, 16, v43
	v_and_b32_e32 v43, 0xffff0000, v43
	v_pk_add_f32 v[58:59], v[58:59], v[40:41]
	v_pk_add_f32 v[56:57], v[56:57], v[64:65]
	v_pk_add_f32 v[64:65], v[54:55], v[42:43]
	v_pk_add_f32 v[66:67], v[52:53], v[66:67]
	v_cvt_pk_bf16_f32 v40, v56, v57
	v_cvt_pk_bf16_f32 v41, v58, v59
	v_mul_f32_e32 v57, v57, v57
	v_cvt_pk_bf16_f32 v42, v66, v67
	v_cvt_pk_bf16_f32 v43, v64, v65
	v_mov_b32_e32 v52, v216
	v_mov_b32_e32 v53, v217
	v_mov_b32_e32 v54, v218
	v_mov_b32_e32 v55, v219
	v_mul_f32_e32 v59, v59, v59
	v_mul_f32_e32 v62, v67, v67
	v_mul_f32_e32 v63, v65, v65
	v_fmac_f32_e32 v57, v56, v56
	v_fmac_f32_e32 v59, v58, v58
	v_fmac_f32_e32 v62, v66, v66
	v_fmac_f32_e32 v63, v64, v64
	v_add_f32_e32 v56, v57, v59
	v_add_f32_e32 v57, v62, v63
	v_add_f32_e32 v62, v56, v57
	v_lshlrev_b32_e32 v56, 16, v52
	v_and_b32_e32 v57, 0xffff0000, v52
	v_lshlrev_b32_e32 v52, 16, v53
	v_and_b32_e32 v53, 0xffff0000, v53
	v_lshlrev_b32_e32 v58, 16, v54
	v_and_b32_e32 v59, 0xffff0000, v54
	v_lshlrev_b32_e32 v54, 16, v55
	v_and_b32_e32 v55, 0xffff0000, v55
	v_pk_add_f32 v[50:51], v[50:51], v[52:53]
	v_pk_add_f32 v[48:49], v[48:49], v[56:57]
	v_pk_add_f32 v[46:47], v[46:47], v[54:55]
	v_pk_add_f32 v[44:45], v[44:45], v[58:59]
	v_mul_f32_e32 v52, v49, v49
	v_mul_f32_e32 v53, v51, v51
	v_mul_f32_e32 v54, v45, v45
	v_mul_f32_e32 v55, v47, v47
	v_fmac_f32_e32 v52, v48, v48
	v_fmac_f32_e32 v53, v50, v50
	v_fmac_f32_e32 v54, v44, v44
	v_fmac_f32_e32 v55, v46, v46
	v_add_f32_e32 v52, v52, v53
	v_add_f32_e32 v53, v54, v55
	v_add_f32_e32 v52, v52, v53
	v_add_f32_e32 v54, v62, v52
	ds_bpermute_b32 v55, v27, v54
	v_lshl_add_u64 v[52:53], s[12:13], 0, v[60:61]
	v_lshl_add_u64 v[52:53], v[52:53], 0, v[16:17]
	global_store_dwordx4 v[52:53], v[40:43], off
	s_waitcnt lgkmcnt(0)
	s_nop 0
	v_add_f32_e32 v40, v54, v55
	ds_bpermute_b32 v41, v19, v40
	v_cvt_pk_bf16_f32 v42, v48, v49
	v_cvt_pk_bf16_f32 v43, v50, v51
	v_cvt_pk_bf16_f32 v44, v44, v45
	v_cvt_pk_bf16_f32 v45, v46, v47
	global_store_dwordx4 v[52:53], v[42:45], off offset:256
	s_and_saveexec_b64 s[0:1], vcc
	s_cbranch_execz .LBB0_1982
	s_waitcnt lgkmcnt(0)
	v_add_f32_e32 v40, v40, v41
	ds_write_b32 v26, v40 offset:2304
; __device__ __forceinline__ float sq4(const f32x4 v) { return (v[0] * v[0] + v[1] * v[1]) + (v[2] * v[2] + v[3] * v[3]); }
; __device__ __forceinline__ u32x4 pack8(const f32x4 a, const f32x4 b) { u32x4 w; w.x = cvt_pk_bf16(a[0], a[1]); w.y = cvt_pk_bf16(a[2], a[3]); w.z = cvt_pk_bf16(b[0], b[1]); w.w = cvt_pk_bf16(b[2], b[3]); return w; }
;     __device__ __forceinline__ void operator()(const f32x4 (&acc)[2][2][4][2], const Unit& u, int wr_, int wc_, int fr_, int fq_) const {
;     ...
; #pragma unroll
;         for (int ai = 0; ai < 2; ++ai)
; #pragma unroll
;             for (int m = 0; m < 4; ++m) {
;                 const int row = u.pm * BM + ai * HALF + wr * 64 + m * 16 + fr; const size_t off = (size_t)row * 1024 + col0;
;                 float s = 0.f;
; #pragma unroll
;                 for (int bj = 0; bj < 2; ++bj) {
;                     f32x4 b0, b1;
;                     const size_t boff = (size_t)row * base_ld + col0 + bj * HALF;
;                     if (BASE_BF16) unpack8(*(const u32x4*)((const bf16_t*)base + boff), b0, b1);
;                     else { b0 = *(const f32x4*)((const float*)base + boff); b1 = *(const f32x4*)((const float*)base + boff + 4); }
;                     const f32x4 h0 = b0 + acc[ai][bj][m][0] * ascale, h1 = b1 + acc[ai][bj][m][1] * ascale;
;                     st16_wt((hb + (size_t)row * hb_ld + col0 + bj * HALF), pack8(h0, h1));
;                     s += sq4(h0) + sq4(h1);
;                 }
;                 s += __shfl_xor(s, 16); s += __shfl_xor(s, 32);
;                 if (fq == 0) xw[(ai * HALF + m * 16) * 4] = s;
;             }
.LBB0_1982:
	s_or_b64 exec, exec, s[0:1]
	v_add_u32_e32 v44, 0xa0, v18
	v_ashrrev_i32_e32 v45, 31, v44
	s_waitcnt lgkmcnt(0)
	v_lshlrev_b64 v[40:41], 12, v[44:45]
	v_lshl_add_u64 v[40:41], s[10:11], 0, v[40:41]
	v_lshl_add_u64 v[46:47], v[40:41], 0, v[16:17]
	v_mov_b32_e32 v40, v220
	v_mov_b32_e32 v41, v221
	v_mov_b32_e32 v42, v222
	v_mov_b32_e32 v43, v223
	v_lshlrev_b64 v[44:45], 11, v[44:45]
	v_lshlrev_b32_e32 v48, 16, v40
	v_and_b32_e32 v49, 0xffff0000, v40
	v_lshlrev_b32_e32 v40, 16, v41
	v_and_b32_e32 v41, 0xffff0000, v41
	v_lshlrev_b32_e32 v50, 16, v42
	v_and_b32_e32 v51, 0xffff0000, v42
	v_lshlrev_b32_e32 v42, 16, v43
	v_and_b32_e32 v43, 0xffff0000, v43
	v_pk_add_f32 v[40:41], v[38:39], v[40:41]
	v_pk_add_f32 v[48:49], v[36:37], v[48:49]
	v_pk_add_f32 v[42:43], v[34:35], v[42:43]
	v_pk_add_f32 v[50:51], v[32:33], v[50:51]
	v_cvt_pk_bf16_f32 v32, v48, v49
	v_cvt_pk_bf16_f32 v33, v40, v41
	v_mul_f32_e32 v41, v41, v41
	v_cvt_pk_bf16_f32 v34, v50, v51
	v_cvt_pk_bf16_f32 v35, v42, v43
	v_mov_b32_e32 v36, v224
	v_mov_b32_e32 v37, v225
	v_mov_b32_e32 v38, v226
	v_mov_b32_e32 v39, v227
	v_mul_f32_e32 v46, v49, v49
	v_mul_f32_e32 v47, v51, v51
	v_mul_f32_e32 v43, v43, v43
	v_fmac_f32_e32 v46, v48, v48
	v_fmac_f32_e32 v41, v40, v40
	v_fmac_f32_e32 v47, v50, v50
	v_fmac_f32_e32 v43, v42, v42
	v_add_f32_e32 v40, v46, v41
	v_add_f32_e32 v41, v47, v43
	v_add_f32_e32 v46, v40, v41
	v_lshlrev_b32_e32 v40, 16, v36
	v_and_b32_e32 v41, 0xffff0000, v36
	v_lshlrev_b32_e32 v36, 16, v37
	v_and_b32_e32 v37, 0xffff0000, v37
	v_lshlrev_b32_e32 v42, 16, v38
	v_and_b32_e32 v43, 0xffff0000, v38
	v_lshlrev_b32_e32 v38, 16, v39
	v_and_b32_e32 v39, 0xffff0000, v39
	v_pk_add_f32 v[30:31], v[30:31], v[36:37]
	v_pk_add_f32 v[28:29], v[28:29], v[40:41]
	v_pk_add_f32 v[22:23], v[22:23], v[38:39]
	v_pk_add_f32 v[36:37], v[20:21], v[42:43]
	v_mul_f32_e32 v20, v29, v29
	v_mul_f32_e32 v21, v31, v31
	v_mul_f32_e32 v38, v37, v37
	v_mul_f32_e32 v39, v23, v23
	v_fmac_f32_e32 v20, v28, v28
	v_fmac_f32_e32 v21, v30, v30
	v_fmac_f32_e32 v38, v36, v36
	v_fmac_f32_e32 v39, v22, v22
	v_add_f32_e32 v20, v20, v21
	v_add_f32_e32 v21, v38, v39
	v_add_f32_e32 v20, v20, v21
	v_add_f32_e32 v40, v46, v20
	ds_bpermute_b32 v41, v27, v40
	v_lshl_add_u64 v[20:21], s[12:13], 0, v[44:45]
	v_lshl_add_u64 v[38:39], v[20:21], 0, v[16:17]
	global_store_dwordx4 v[38:39], v[32:35], off
	v_cvt_pk_bf16_f32 v28, v28, v29
	s_waitcnt lgkmcnt(0)
	v_add_f32_e32 v20, v40, v41
	ds_bpermute_b32 v21, v19, v20
	v_cvt_pk_bf16_f32 v29, v30, v31
	v_cvt_pk_bf16_f32 v30, v36, v37
	v_cvt_pk_bf16_f32 v31, v22, v23
	global_store_dwordx4 v[38:39], v[28:31], off offset:256
	s_and_saveexec_b64 s[0:1], vcc
	s_cbranch_execz .LBB0_1984
	s_waitcnt lgkmcnt(0)
	v_add_f32_e32 v20, v20, v21
	ds_write_b32 v26, v20 offset:2560
.LBB0_1984:
	s_or_b64 exec, exec, s[0:1]
	v_add_u32_e32 v28, 0xb0, v18
	v_ashrrev_i32_e32 v29, 31, v28
	s_waitcnt lgkmcnt(0)
	v_lshlrev_b64 v[20:21], 12, v[28:29]
	v_lshl_add_u64 v[20:21], s[10:11], 0, v[20:21]
	v_lshl_add_u64 v[30:31], v[20:21], 0, v[16:17]
	v_mov_b32_e32 v20, v228
	v_mov_b32_e32 v21, v229
	v_mov_b32_e32 v22, v230
	v_mov_b32_e32 v23, v231
	v_lshlrev_b64 v[28:29], 11, v[28:29]
	v_lshlrev_b32_e32 v32, 16, v20
	v_and_b32_e32 v33, 0xffff0000, v20
	v_lshlrev_b32_e32 v20, 16, v21
	v_and_b32_e32 v21, 0xffff0000, v21
	v_lshlrev_b32_e32 v34, 16, v22
	v_and_b32_e32 v35, 0xffff0000, v22
	v_lshlrev_b32_e32 v22, 16, v23
	v_and_b32_e32 v23, 0xffff0000, v23
	v_pk_add_f32 v[20:21], v[14:15], v[20:21]
	v_pk_add_f32 v[32:33], v[12:13], v[32:33]
	v_pk_add_f32 v[22:23], v[10:11], v[22:23]
	v_pk_add_f32 v[34:35], v[8:9], v[34:35]
	v_cvt_pk_bf16_f32 v8, v32, v33
	v_cvt_pk_bf16_f32 v9, v20, v21
	v_mul_f32_e32 v18, v33, v33
	v_cvt_pk_bf16_f32 v10, v34, v35
	v_cvt_pk_bf16_f32 v11, v22, v23
	v_mov_b32_e32 v12, v232
	v_mov_b32_e32 v13, v233
	v_mov_b32_e32 v14, v234
	v_mov_b32_e32 v15, v235
	v_mul_f32_e32 v21, v21, v21
	v_mul_f32_e32 v30, v35, v35
	v_mul_f32_e32 v23, v23, v23
	v_fmac_f32_e32 v18, v32, v32
	v_fmac_f32_e32 v21, v20, v20
	v_fmac_f32_e32 v30, v34, v34
	v_fmac_f32_e32 v23, v22, v22
	v_add_f32_e32 v18, v18, v21
	v_add_f32_e32 v20, v30, v23
	v_add_f32_e32 v18, v18, v20
	v_lshlrev_b32_e32 v20, 16, v12
	v_and_b32_e32 v21, 0xffff0000, v12
	v_lshlrev_b32_e32 v12, 16, v13
	v_and_b32_e32 v13, 0xffff0000, v13
	v_lshlrev_b32_e32 v22, 16, v14
	v_and_b32_e32 v23, 0xffff0000, v14
	v_lshlrev_b32_e32 v14, 16, v15
	v_and_b32_e32 v15, 0xffff0000, v15
	v_pk_add_f32 v[6:7], v[6:7], v[12:13]
	v_pk_add_f32 v[4:5], v[4:5], v[20:21]
	v_pk_add_f32 v[12:13], v[2:3], v[14:15]
	v_pk_add_f32 v[14:15], v[0:1], v[22:23]
	v_mul_f32_e32 v0, v5, v5
	v_mul_f32_e32 v1, v7, v7
	v_mul_f32_e32 v2, v15, v15
	v_mul_f32_e32 v3, v13, v13
	v_fmac_f32_e32 v0, v4, v4
	v_fmac_f32_e32 v1, v6, v6
	v_fmac_f32_e32 v2, v14, v14
	v_fmac_f32_e32 v3, v12, v12
	v_add_f32_e32 v0, v0, v1
	v_add_f32_e32 v1, v2, v3
	v_add_f32_e32 v0, v0, v1
	v_add_f32_e32 v3, v18, v0
	ds_bpermute_b32 v18, v27, v3
	v_lshl_add_u64 v[0:1], s[12:13], 0, v[28:29]
	v_lshl_add_u64 v[16:17], v[0:1], 0, v[16:17]
	global_store_dwordx4 v[16:17], v[8:11], off
	v_cvt_pk_bf16_f32 v2, v4, v5
	s_waitcnt lgkmcnt(0)
	v_add_f32_e32 v0, v3, v18
	ds_bpermute_b32 v1, v19, v0
	v_cvt_pk_bf16_f32 v3, v6, v7
	v_cvt_pk_bf16_f32 v4, v14, v15
	v_cvt_pk_bf16_f32 v5, v12, v13
	global_store_dwordx4 v[16:17], v[2:5], off offset:256
	s_and_saveexec_b64 s[0:1], vcc
	s_cbranch_execz .LBB0_1986
	s_waitcnt lgkmcnt(0)
	v_add_f32_e32 v0, v0, v1
	ds_write_b32 v26, v0 offset:2816
